# baseline (speedup 1.0000x reference)
; #define LDK(DST, KQ) _Pragma("unroll") for (int kc = 0; kc < 4; ++kc) DST[kc] = *(const bf16x8*)(Ks + ((KQ) * 16 + fr) * 136 + kc * 32 + fq * 8)
; DEVINL void attn_item(const Params& p, int item, char* smem, int wv) {
;     ...
;   const size_t qtok = (size_t)b * SEQ + q0 + wid * 16 + fr;
;   bf16x8 qf[2][4];
; #pragma unroll
;   for (int hh = 0; hh < 2; ++hh)
; #pragma unroll
;     for (int kc = 0; kc < 4; ++kc)
;       qf[hh][kc] = *(const bf16x8*)(hb + qtok * HS + 2560 + (kvh * 2 + hh) * 128 + kc * 32 + fq * 8);
;   f32x4 o[2][8];
; #pragma unroll
;   for (int hh = 0; hh < 2; ++hh)
; #pragma unroll
;     for (int dt = 0; dt < 8; ++dt) o[hh][dt] = f32x4{0.f, 0.f, 0.f, 0.f};
;   float mrun[2] = {0.f, 0.f}, lsum[2] = {0.f, 0.f};
;   unsigned long long mw_next = bits[qtok * 64];
;   u32x4 rk[2], rv[2];
;   const u16* kg = hb + ((size_t)b * SEQ + (tid >> 4)) * HS + 3584 + kvh * 128 + (tid & 15) * 8;
;   const u16* vg = vT + ((size_t)(b * 4 + kvh) * 128 + (tid >> 3)) * SEQ + (tid & 7) * 8;
; #pragma unroll
;   for (int i = 0; i < 2; ++i) {
;     rk[i] = *(const u32x4*)(kg + (size_t)(32 * i) * HS);
;     rv[i] = *(const u32x4*)(vg + (size_t)(64 * i) * SEQ);
;   }
;   for (int kt = 0; kt < ntile; ++kt) {
; #pragma unroll
;     for (int i = 0; i < 2; ++i) {
;       *(u32x4*)(Ks + ((tid >> 4) + 32 * i) * 136 + (tid & 15) * 8) = rk[i];
;       *(u32x4*)(Vs + ((tid >> 3) + 64 * i) * 72 + (tid & 7) * 8) = rv[i];
;     }
;     __syncthreads();
;     if (kt + 1 < ntile) {
; #pragma unroll
;       for (int i = 0; i < 2; ++i) {
;         rk[i] = *(const u32x4*)(kg + (size_t)((kt + 1) * 64 + 32 * i) * HS);
;         rv[i] = *(const u32x4*)(vg + (size_t)(64 * i) * SEQ + (kt + 1) * 64);
;       }
;     }
;     const unsigned long long mw = mw_next;
;     if (kt + 1 < ntile) mw_next = bits[qtok * 64 + kt + 1];
;     if (kt * 64 <= qlast) {
;     f32x4 s[2][4];
;     bf16x8 kfa[4], kfb[4];
;     bf16x8 vfa[2], vfb[2];
;     ...
;     LDK(kfa, 0);
;     LDK(kfb, 1); MMS(kfa, 0);
;     LDK(kfa, 2); MMS(kfb, 1);
;     LDK(kfb, 3); MMS(kfa, 2);
;     LDV(vfa, 0); MMS(kfb, 3);
.Lprio_skip_a0:
	s_and_b32 s33, s1, 0x3000
	v_and_b32_e32 v60, 15, v120
	s_and_b32 s0, s31, -16
	s_add_i32 s8, s7, s33
	s_ashr_i32 s1, s0, 31
	v_or_b32_e32 v0, s8, v60
	s_waitcnt vmcnt(1)
	v_lshl_add_u64 v[156:157], v[0:1], 0, s[0:1]
	v_mov_b64_e32 v[2:3], s[62:63]
	v_mad_u64_u32 v[4:5], s[0:1], v156, s19, v[2:3]
	s_and_b32 s6, s5, 3
	v_mad_i32_i24 v5, v157, s19, v5
	v_and_b32_e32 v0, 48, v120
	v_lshl_add_u64 v[4:5], v[4:5], 0, v[0:1]
	s_lshl_b32 s8, s6, 9
	v_ashrrev_i32_e32 v14, 4, v120
	v_lshl_add_u64 v[8:9], v[4:5], 0, s[8:9]
	v_add_u32_e32 v4, s33, v14
	s_lshl_b32 s16, s6, 8
	s_mov_b32 s17, s9
	v_mad_i64_i32 v[2:3], s[0:1], v4, s19, v[2:3]
	v_lshlrev_b32_e32 v6, 4, v120
	v_lshl_add_u64 v[2:3], v[2:3], 0, s[16:17]
	v_and_b32_e32 v10, 0xf0, v6
	v_mov_b32_e32 v11, v1
	v_lshl_add_u64 v[116:117], v[2:3], 0, v[10:11]
	s_lshl_b32 s0, s5, 7
	v_ashrrev_i32_e32 v2, 3, v120
	s_and_b32 s8, s0, 0x780
	v_ashrrev_i32_e32 v3, 31, v2
	v_lshl_add_u64 v[4:5], v[2:3], 0, s[8:9]
	v_lshlrev_b64 v[4:5], 13, v[4:5]
	v_lshl_add_u64 v[4:5], s[82:83], 0, v[4:5]
	v_and_b32_e32 v12, 0x70, v6
	v_mov_b32_e32 v13, v1
	v_lshl_add_u64 v[158:159], v[4:5], 0, v[12:13]
	v_add_co_u32_e32 v4, vcc, s20, v116
	global_load_dwordx4 v[36:39], v[158:159], off
	s_nop 0
	v_addc_co_u32_e32 v5, vcc, 0, v117, vcc
	v_add_co_u32_e32 v6, vcc, s21, v116
	v_mul_lo_u32 v2, v2, s24
	s_nop 0
	v_addc_co_u32_e32 v7, vcc, 0, v117, vcc
	global_load_dwordx4 v[40:43], v[4:5], off offset:3072
	global_load_dwordx4 v[44:47], v[6:7], off offset:3072
	v_add_co_u32_e32 v52, vcc, s22, v158
	v_add_u32_e32 v11, 0, v12
	s_nop 0
	v_addc_co_u32_e32 v53, vcc, 0, v159, vcc
	global_load_dwordx4 v[48:51], v[52:53], off
	v_mul_lo_u32 v3, v14, s23
	v_add_u32_e32 v10, 0, v10
	v_and_b32_e32 v173, 64, v12
	v_bfe_u32 v11, v12, 4, 1
	v_lshl_or_b32 v173, v11, 5, v173
	v_bfe_u32 v11, v12, 5, 1
	v_lshl_or_b32 v173, v11, 3, v173
	v_add_u32_e32 v173, v173, v2
	v_add_co_u32_e64 v2, s[0:1], s20, v8
	v_lshl_add_u64 v[28:29], v[8:9], 0, s[10:11]
	v_add_u32_e32 v172, v10, v3
	v_lshlrev_b64 v[118:119], 9, v[156:157]
	v_add_co_u32_e32 v54, vcc, 0xa1000, v116
	v_addc_co_u32_e64 v3, s[0:1], 0, v9, s[0:1]
	global_load_dwordx4 v[4:7], v[28:29], off offset:64
	v_lshl_add_u64 v[56:57], s[80:81], 0, v[118:119]
	v_addc_co_u32_e32 v55, vcc, 0, v117, vcc
	global_load_dwordx4 v[8:11], v[28:29], off offset:128
	global_load_dwordx4 v[12:15], v[28:29], off offset:192
	global_load_dwordx4 v[16:19], v[28:29], off offset:256
	global_load_dwordx4 v[20:23], v[28:29], off offset:320
	global_load_dwordx4 v[24:27], v[28:29], off offset:384
	s_nop 0
	global_load_dwordx4 v[28:31], v[28:29], off offset:448
	s_nop 0
	global_load_dwordx4 v[32:35], v[2:3], off offset:1024
	s_nop 0
	global_load_dwordx2 v[2:3], v[56:57], off
	v_add_co_u32_e32 v58, vcc, 0xf1000, v116
	s_add_i32 s8, s31, s7
	s_nop 0
	v_addc_co_u32_e32 v59, vcc, 0, v117, vcc
	s_cmp_gt_i32 s8, -1
	s_mov_b64 s[0:1], -1
	s_waitcnt vmcnt(11)
	ds_write_b128 v172, v[40:43]
	ds_write_b64 v173, v[36:37] offset:17408
	ds_write_b64 v173, v[38:39] offset:17424
	s_waitcnt vmcnt(10)
	ds_write_b128 v172, v[44:47] offset:8704
	s_waitcnt vmcnt(9)
	ds_write_b64 v173, v[48:49] offset:26624
	ds_write_b64 v173, v[50:51] offset:26640
	s_waitcnt lgkmcnt(0)
	s_barrier
	global_load_dwordx4 v[44:47], v[58:59], off offset:3072
	global_load_dwordx4 v[36:39], v[54:55], off offset:3072
	global_load_dwordx4 v[48:51], v[52:53], off offset:128
	global_load_dwordx4 v[40:43], v[158:159], off offset:128
	global_load_dwordx2 v[162:163], v[56:57], off offset:8
	v_mad_u32_u24 v52, v60, s23, 0
	v_lshlrev_b32_e32 v53, 7, v60
	v_lshrrev_b32_e32 v54, 2, v120
	v_sub_u32_e32 v53, v52, v53
	v_and_b32_e32 v174, 12, v54
	v_add_u32_e32 v175, v52, v0
	v_lshl_add_u32 v177, v174, 2, v53
	s_cbranch_scc0 .LBB0_704
	ds_read_b128 v[52:55], v175
	ds_read_b128 v[56:59], v175 offset:64
	ds_read_b128 v[60:63], v175 offset:128
	ds_read_b128 v[64:67], v175 offset:192
	ds_read_b128 v[68:71], v175 offset:4352
	ds_read_b128 v[72:75], v175 offset:4416
	ds_read_b128 v[76:79], v175 offset:4480
	ds_read_b128 v[80:83], v175 offset:4544
	s_mov_b32 s6, s4
	s_mov_b32 s7, s4
	s_mov_b32 s5, s4
	v_mov_b64_e32 v[86:87], s[6:7]
	v_mov_b64_e32 v[84:85], s[4:5]
	s_waitcnt vmcnt(6) lgkmcnt(7)
	s_nop 0
	v_mfma_f32_16x16x32_bf16 v[88:91], v[52:55], v[32:35], v[84:87]
	v_mfma_f32_16x16x32_bf16 v[52:55], v[52:55], v[16:19], v[84:87]
	s_waitcnt lgkmcnt(4)
	v_mfma_f32_16x16x32_bf16 v[88:91], v[56:59], v[4:7], v[88:91]
	v_mfma_f32_16x16x32_bf16 v[52:55], v[56:59], v[20:23], v[52:55]
	v_mfma_f32_16x16x32_bf16 v[56:59], v[60:63], v[8:11], v[88:91]
	v_mfma_f32_16x16x32_bf16 v[52:55], v[60:63], v[24:27], v[52:55]
	v_mfma_f32_16x16x32_bf16 v[60:63], v[64:67], v[12:15], v[56:59]
	v_mfma_f32_16x16x32_bf16 v[64:67], v[64:67], v[28:31], v[52:55]
	s_nop 3
	s_nop 1
	ds_read_b128 v[52:55], v175 offset:8704
	ds_read_b128 v[56:59], v175 offset:8768
	ds_read_b128 v[88:91], v175 offset:8832
	ds_read_b128 v[92:95], v175 offset:8896
	s_waitcnt lgkmcnt(4)
	v_mfma_f32_16x16x32_bf16 v[96:99], v[68:71], v[32:35], v[84:87]
	v_mfma_f32_16x16x32_bf16 v[68:71], v[68:71], v[16:19], v[84:87]
	v_mfma_f32_16x16x32_bf16 v[96:99], v[72:75], v[4:7], v[96:99]
	v_mfma_f32_16x16x32_bf16 v[68:71], v[72:75], v[20:23], v[68:71]
	v_mfma_f32_16x16x32_bf16 v[72:75], v[76:79], v[8:11], v[96:99]
	v_mfma_f32_16x16x32_bf16 v[68:71], v[76:79], v[24:27], v[68:71]
	v_mfma_f32_16x16x32_bf16 v[72:75], v[80:83], v[12:15], v[72:75]
	v_mfma_f32_16x16x32_bf16 v[68:71], v[80:83], v[28:31], v[68:71]
	ds_read_b128 v[76:79], v175 offset:13056
	ds_read_b128 v[80:83], v175 offset:13120
	s_nop 0
	ds_read_b128 v[96:99], v175 offset:13184
	ds_read_b128 v[100:103], v175 offset:13248
	s_waitcnt lgkmcnt(4)
; DEVINL float fexp2(float x) { return __builtin_amdgcn_exp2f(x); }
; #define LDK(DST, KQ) _Pragma("unroll") for (int kc = 0; kc < 4; ++kc) DST[kc] = *(const bf16x8*)(Ks + ((KQ) * 16 + fr) * 136 + kc * 32 + fq * 8)
; DEVINL void attn_item(const Params& p, int item, char* smem, int wv) {
;     ...
;     LDK(kfb, 1); MMS(kfa, 0);
;     LDK(kfa, 2); MMS(kfb, 1);
;     LDK(kfb, 3); MMS(kfa, 2);
;     LDV(vfa, 0); MMS(kfb, 3);
;     bf16x8 pf[2][2];
;     {
;       const unsigned long long msh = mw >> (fq * 4);
;       const int mlo = (int)(unsigned)msh, mhi = (int)(unsigned)(msh >> 32);
;       int mk[4][4];
; #pragma unroll
;       for (int j = 0; j < 4; ++j) {
;         mk[0][j] = __builtin_amdgcn_sbfe(mlo, j, 1); mk[1][j] = __builtin_amdgcn_sbfe(mlo, 16 + j, 1);
;         mk[2][j] = __builtin_amdgcn_sbfe(mhi, j, 1); mk[3][j] = __builtin_amdgcn_sbfe(mhi, 16 + j, 1);
;       }
; #pragma unroll
;       for (int hh = 0; hh < 2; ++hh) {
;         float mx = s[hh][0][0];
; #pragma unroll
;         for (int kq = 0; kq < 4; ++kq)
; #pragma unroll
;           for (int j = 0; j < 4; ++j) mx = fmaxf(mx, s[hh][kq][j]);
;         {
;           auto r1 = __builtin_amdgcn_permlane16_swap(__float_as_uint(mx), __float_as_uint(mx), false, false);
;           mx = fmaxf(__uint_as_float(r1[0]), __uint_as_float(r1[1]));
;           auto r2 = __builtin_amdgcn_permlane32_swap(__float_as_uint(mx), __float_as_uint(mx), false, false);
;           mx = fmaxf(__uint_as_float(r2[0]), __uint_as_float(r2[1]));
;         }
;         if (kt == 0 || __ballot(mx > 8.f)) {
;           const float delta = (kt == 0) ? mx : fmaxf(mx, 0.f);
;           const float alpha = fexp2(-delta);
;           mrun[hh] += delta;
;           lsum[hh] *= alpha;
; #pragma unroll
;           for (int dt = 0; dt < 8; ++dt) o[hh][dt] *= alpha;
; #pragma unroll
;           for (int kq = 0; kq < 4; ++kq)
; #pragma unroll
;             for (int j = 0; j < 4; ++j) s[hh][kq][j] -= delta;
;         }
;         float ps = 0.f;
;         float pv[4][4];
; #pragma unroll
;         for (int kq = 0; kq < 4; ++kq)
; #pragma unroll
;           for (int j = 0; j < 4; ++j) {
;             pv[kq][j] = __uint_as_float(__float_as_uint(fexp2(s[hh][kq][j])) & (unsigned)mk[kq][j]);
;             ps += pv[kq][j];
;           }
	v_mfma_f32_16x16x32_bf16 v[104:107], v[52:55], v[32:35], v[84:87]
	v_mfma_f32_16x16x32_bf16 v[52:55], v[52:55], v[16:19], v[84:87]
	v_mfma_f32_16x16x32_bf16 v[104:107], v[56:59], v[4:7], v[104:107]
	v_mfma_f32_16x16x32_bf16 v[52:55], v[56:59], v[20:23], v[52:55]
	v_mfma_f32_16x16x32_bf16 v[56:59], v[88:91], v[8:11], v[104:107]
	v_mfma_f32_16x16x32_bf16 v[52:55], v[88:91], v[24:27], v[52:55]
	v_mfma_f32_16x16x32_bf16 v[88:91], v[92:95], v[12:15], v[56:59]
	v_mfma_f32_16x16x32_bf16 v[92:95], v[92:95], v[28:31], v[52:55]
	s_nop 2
	s_nop 0
	s_nop 1
	ds_read_b128 v[52:55], v177 offset:17408
	ds_read_b128 v[56:59], v177 offset:17472
	s_waitcnt lgkmcnt(2)
	v_mfma_f32_16x16x32_bf16 v[104:107], v[76:79], v[32:35], v[84:87]
	v_mfma_f32_16x16x32_bf16 v[76:79], v[76:79], v[16:19], v[84:87]
	v_mfma_f32_16x16x32_bf16 v[84:87], v[80:83], v[4:7], v[104:107]
	v_mfma_f32_16x16x32_bf16 v[76:79], v[80:83], v[20:23], v[76:79]
	v_mfma_f32_16x16x32_bf16 v[80:83], v[96:99], v[8:11], v[84:87]
	v_mfma_f32_16x16x32_bf16 v[76:79], v[96:99], v[24:27], v[76:79]
	v_mfma_f32_16x16x32_bf16 v[80:83], v[100:103], v[12:15], v[80:83]
	v_mfma_f32_16x16x32_bf16 v[76:79], v[100:103], v[28:31], v[76:79]
	s_waitcnt vmcnt(5)
	v_lshrrev_b64 v[2:3], v174, v[2:3]
	v_bfe_i32 v0, v2, 0, 1
	v_bfe_i32 v86, v2, 16, 1
	v_bfe_i32 v87, v3, 0, 1
	v_bfe_i32 v96, v3, 16, 1
	v_bfe_i32 v97, v2, 1, 1
	v_bfe_i32 v98, v2, 17, 1
	v_bfe_i32 v99, v3, 1, 1
	v_bfe_i32 v104, v3, 17, 1
	v_bfe_i32 v100, v2, 2, 1
	v_bfe_i32 v101, v2, 18, 1
	v_bfe_i32 v105, v3, 2, 1
	v_bfe_i32 v106, v3, 18, 1
	v_bfe_i32 v102, v2, 3, 1
	v_bfe_i32 v103, v2, 19, 1
	v_bfe_i32 v107, v3, 3, 1
	v_bfe_i32 v108, v3, 19, 1
	v_max_f32_e32 v3, v60, v60
	v_max_f32_e32 v2, v3, v61
	v_max3_f32 v2, v2, v62, v63
	v_max3_f32 v2, v2, v72, v73
	v_max3_f32 v2, v2, v74, v75
	v_max3_f32 v2, v2, v88, v89
	v_max3_f32 v2, v2, v90, v91
	v_max3_f32 v2, v2, v80, v81
	v_max3_f32 v2, v2, v82, v83
	v_mov_b32_e32 v3, v2
	s_nop 1
	v_permlane16_swap_b32_e32 v2, v3
	v_max_f32_e32 v2, v2, v3
	v_mov_b32_e32 v3, v2
	s_nop 1
	v_permlane32_swap_b32_e32 v2, v3
	v_max_f32_e32 v3, v2, v3
	v_sub_f32_e32 v2, v80, v3
	v_sub_f32_e32 v61, v61, v3
	v_sub_f32_e32 v80, v81, v3
	v_sub_f32_e32 v81, v82, v3
	v_sub_f32_e32 v82, v83, v3
	v_sub_f32_e32 v83, v88, v3
	v_sub_f32_e32 v88, v90, v3
	v_exp_f32_e32 v90, v61
	v_exp_f32_e32 v115, v2
	v_max_f32_e32 v61, v64, v64
	v_max_f32_e32 v2, v61, v65
	v_max3_f32 v2, v2, v66, v67
	v_max3_f32 v2, v2, v68, v69
	v_max3_f32 v2, v2, v70, v71
	v_max3_f32 v2, v2, v92, v93
	v_max3_f32 v2, v2, v94, v95
	v_max3_f32 v2, v2, v76, v77
	v_max3_f32 v2, v2, v78, v79
	v_mov_b32_e32 v61, v2
	s_nop 1
	v_permlane16_swap_b32_e32 v2, v61
	v_max_f32_e32 v2, v2, v61
	v_mov_b32_e32 v61, v2
	s_nop 1
	v_permlane32_swap_b32_e32 v2, v61
	v_max_f32_e32 v2, v2, v61
	v_sub_f32_e32 v60, v60, v3
	v_sub_f32_e32 v64, v64, v2
	v_exp_f32_e32 v60, v60
	v_sub_f32_e32 v65, v65, v2
	v_exp_f32_e32 v64, v64
	v_sub_f32_e32 v62, v62, v3
	v_sub_f32_e32 v66, v66, v2
	v_exp_f32_e32 v65, v65
	v_sub_f32_e32 v85, v89, v3
	v_sub_f32_e32 v89, v91, v3
	v_sub_f32_e32 v63, v63, v3
	v_exp_f32_e32 v91, v62
	v_sub_f32_e32 v67, v67, v2
	v_exp_f32_e32 v66, v66
	v_sub_f32_e32 v72, v72, v3
	v_exp_f32_e32 v109, v63
	v_sub_f32_e32 v61, v68, v2
	v_sub_f32_e32 v62, v69, v2
	v_exp_f32_e32 v67, v67
	v_sub_f32_e32 v73, v73, v3
	v_exp_f32_e32 v72, v72
	v_exp_f32_e32 v113, v83
	v_exp_f32_e32 v125, v82
	v_sub_f32_e32 v82, v92, v2
	v_sub_f32_e32 v83, v93, v2
	v_sub_f32_e32 v63, v70, v2
	v_sub_f32_e32 v68, v71, v2
	v_exp_f32_e32 v70, v61
	v_exp_f32_e32 v71, v62
	v_and_b32_e32 v61, v0, v64
	v_and_b32_e32 v60, v0, v60
	v_and_b32_e32 v62, v97, v90
	v_sub_f32_e32 v74, v74, v3
	v_exp_f32_e32 v110, v73
	v_exp_f32_e32 v121, v80
	v_exp_f32_e32 v124, v81
	v_sub_f32_e32 v122, v76, v2
	v_sub_f32_e32 v126, v78, v2
	v_exp_f32_e32 v76, v63
	v_exp_f32_e32 v78, v68
	v_and_b32_e32 v63, v97, v65
	v_cvt_pk_bf16_f32 v68, v60, v62
	v_pk_add_f32 v[80:81], v[60:61], 0 op_sel_hi:[1,0]
	v_exp_f32_e32 v0, v82
	v_exp_f32_e32 v60, v83
	v_sub_f32_e32 v75, v75, v3
	v_exp_f32_e32 v111, v74
	v_and_b32_e32 v65, v100, v66
	v_and_b32_e32 v64, v100, v91
	v_pk_add_f32 v[80:81], v[80:81], v[62:63]
	v_exp_f32_e32 v112, v75
	v_and_b32_e32 v67, v102, v67
	v_and_b32_e32 v66, v102, v109
	v_pk_add_f32 v[80:81], v[80:81], v[64:65]
	v_sub_f32_e32 v93, v95, v2
	v_and_b32_e32 v73, v86, v70
	v_and_b32_e32 v72, v86, v72
	v_pk_add_f32 v[80:81], v[80:81], v[66:67]
	v_exp_f32_e32 v114, v85
	v_sub_f32_e32 v92, v94, v2
	v_and_b32_e32 v75, v98, v71
	v_and_b32_e32 v74, v98, v110
	v_pk_add_f32 v[80:81], v[80:81], v[72:73]
	v_and_b32_e32 v83, v87, v0
	v_and_b32_e32 v82, v87, v113
	v_and_b32_e32 v87, v99, v60
	v_exp_f32_e32 v60, v93
	v_exp_f32_e32 v88, v88
	v_sub_f32_e32 v123, v77, v2
	v_and_b32_e32 v77, v101, v76
	v_and_b32_e32 v76, v101, v111
	v_pk_add_f32 v[80:81], v[80:81], v[74:75]
	v_exp_f32_e32 v0, v92
	v_exp_f32_e32 v89, v89
	v_sub_f32_e32 v127, v79, v2
	v_and_b32_e32 v79, v103, v78
	v_and_b32_e32 v78, v103, v112
	v_pk_add_f32 v[80:81], v[80:81], v[76:77]
	v_exp_f32_e32 v62, v122
	v_pk_add_f32 v[80:81], v[80:81], v[78:79]
	v_cvt_pk_bf16_f32 v69, v64, v66
	v_and_b32_e32 v86, v99, v114
	v_exp_f32_e32 v64, v123
	v_cvt_pk_bf16_f32 v100, v61, v63
	v_cvt_pk_bf16_f32 v102, v73, v75
	v_and_b32_e32 v75, v107, v60
	v_pk_add_f32 v[60:61], v[80:81], v[82:83]
	v_cvt_pk_bf16_f32 v70, v72, v74
	v_exp_f32_e32 v66, v126
	v_and_b32_e32 v73, v105, v0
	v_and_b32_e32 v72, v105, v88
	v_pk_add_f32 v[60:61], v[60:61], v[86:87]
	v_exp_f32_e32 v90, v127
	v_and_b32_e32 v74, v107, v89
	v_pk_add_f32 v[60:61], v[60:61], v[72:73]
	v_cvt_pk_bf16_f32 v71, v76, v78
	v_cvt_pk_bf16_f32 v103, v77, v79
	v_and_b32_e32 v77, v96, v62
	v_and_b32_e32 v76, v96, v115
	v_pk_add_f32 v[60:61], v[60:61], v[74:75]
	v_and_b32_e32 v79, v104, v64
	v_and_b32_e32 v78, v104, v121
	v_pk_add_f32 v[60:61], v[60:61], v[76:77]
	v_and_b32_e32 v89, v106, v66
	v_and_b32_e32 v88, v106, v124
	v_pk_add_f32 v[60:61], v[60:61], v[78:79]
	v_and_b32_e32 v91, v108, v90
	v_and_b32_e32 v90, v108, v125
	v_pk_add_f32 v[60:61], v[60:61], v[88:89]
	v_exp_f32_e64 v84, -v3
	v_exp_f32_e64 v85, -v2
	v_cvt_pk_bf16_f32 v101, v65, v67
	v_pk_add_f32 v[80:81], v[60:61], v[90:91]
	ds_read_b128 v[60:63], v177 offset:19712
	ds_read_b128 v[64:67], v177 offset:19776
	v_pk_add_f32 v[2:3], v[2:3], 0 op_sel_hi:[1,0]
	v_pk_mul_f32 v[122:123], v[84:85], 0 op_sel_hi:[1,0]
	v_pk_fma_f32 v[160:161], v[84:85], 0, v[80:81] op_sel_hi:[1,0,1]
	v_mov_b32_e32 v126, v122
	v_mov_b32_e32 v127, v122
	v_mov_b32_e32 v128, v122
	v_mov_b32_e32 v129, v122
	v_cvt_pk_bf16_f32 v130, v82, v86
	v_cvt_pk_bf16_f32 v131, v72, v74
	v_cvt_pk_bf16_f32 v132, v76, v78
	v_cvt_pk_bf16_f32 v133, v88, v90
	v_mov_b32_e32 v122, v123
	v_mov_b32_e32 v124, v123
	v_mov_b32_e32 v125, v123
	v_cvt_pk_bf16_f32 v134, v83, v87
	v_cvt_pk_bf16_f32 v135, v73, v75
	v_cvt_pk_bf16_f32 v136, v77, v79
	v_cvt_pk_bf16_f32 v137, v89, v91
	s_waitcnt lgkmcnt(2)
; #define MMV(SRC, DT) do { __builtin_amdgcn_s_setprio(1); _Pragma("unroll") for (int c2 = 0; c2 < 2; ++c2) { o[0][DT] = mfma16(SRC[c2], pf[0][c2], o[0][DT]); o[1][DT] = mfma16(SRC[c2], pf[1][c2], o[1][DT]); } __builtin_amdgcn_s_setprio(0); } while (0)
; DEVINL void attn_item(const Params& p, int item, char* smem, int wv) {
;     ...
;     LDV(vfb, 1); MMV(vfa, 0);
;     LDV(vfa, 2); MMV(vfb, 1);
;     LDV(vfb, 3); MMV(vfa, 2);
;     LDV(vfa, 4); MMV(vfb, 3);
;     LDV(vfb, 5); MMV(vfa, 4);
;     LDV(vfa, 6); MMV(vfb, 5);
;     LDV(vfb, 7); MMV(vfa, 6);
;     MMV(vfb, 7);
	v_mfma_f32_16x16x32_bf16 v[72:75], v[52:55], v[68:71], v[126:129]
	v_mfma_f32_16x16x32_bf16 v[52:55], v[52:55], v[100:103], v[122:125]
	v_mfma_f32_16x16x32_bf16 v[88:91], v[56:59], v[130:133], v[72:75]
	v_mfma_f32_16x16x32_bf16 v[52:55], v[56:59], v[134:137], v[52:55]
	s_nop 1
	s_nop 2
	ds_read_b128 v[72:75], v177 offset:22016
	ds_read_b128 v[76:79], v177 offset:22080
	s_waitcnt lgkmcnt(2)
	v_mfma_f32_16x16x32_bf16 v[56:59], v[60:63], v[68:71], v[126:129]
	v_mfma_f32_16x16x32_bf16 v[60:63], v[60:63], v[100:103], v[122:125]
	v_mfma_f32_16x16x32_bf16 v[84:87], v[64:67], v[130:133], v[56:59]
	v_mfma_f32_16x16x32_bf16 v[56:59], v[64:67], v[134:137], v[60:63]
	ds_read_b128 v[64:67], v177 offset:24320
	ds_read_b128 v[80:83], v177 offset:24384
	s_waitcnt lgkmcnt(2)
	v_mfma_f32_16x16x32_bf16 v[60:63], v[72:75], v[68:71], v[126:129]
	v_mfma_f32_16x16x32_bf16 v[72:75], v[72:75], v[100:103], v[122:125]
	v_mfma_f32_16x16x32_bf16 v[92:95], v[76:79], v[130:133], v[60:63]
	v_mfma_f32_16x16x32_bf16 v[60:63], v[76:79], v[134:137], v[72:75]
	s_nop 2
	s_nop 2
	ds_read_b128 v[72:75], v177 offset:26624
	ds_read_b128 v[76:79], v177 offset:26688
	s_waitcnt lgkmcnt(2)
	v_mfma_f32_16x16x32_bf16 v[96:99], v[64:67], v[68:71], v[126:129]
	v_mfma_f32_16x16x32_bf16 v[64:67], v[64:67], v[100:103], v[122:125]
	v_mfma_f32_16x16x32_bf16 v[96:99], v[80:83], v[130:133], v[96:99]
	v_mfma_f32_16x16x32_bf16 v[64:67], v[80:83], v[134:137], v[64:67]
	ds_read_b128 v[80:83], v177 offset:28928
	ds_read_b128 v[112:115], v177 offset:28992
	s_waitcnt lgkmcnt(2)
	v_mfma_f32_16x16x32_bf16 v[104:107], v[72:75], v[68:71], v[126:129]
	v_mfma_f32_16x16x32_bf16 v[72:75], v[72:75], v[100:103], v[122:125]
	v_mfma_f32_16x16x32_bf16 v[104:107], v[76:79], v[130:133], v[104:107]
	v_mfma_f32_16x16x32_bf16 v[72:75], v[76:79], v[134:137], v[72:75]
	ds_read_b128 v[138:141], v177 offset:31232
	ds_read_b128 v[142:145], v177 offset:31296
	s_waitcnt lgkmcnt(2)
	v_mfma_f32_16x16x32_bf16 v[76:79], v[80:83], v[68:71], v[126:129]
	v_mfma_f32_16x16x32_bf16 v[80:83], v[80:83], v[100:103], v[122:125]
	v_mfma_f32_16x16x32_bf16 v[108:111], v[112:115], v[130:133], v[76:79]
	v_mfma_f32_16x16x32_bf16 v[76:79], v[112:115], v[134:137], v[80:83]
	ds_read_b128 v[146:149], v177 offset:33536
	ds_read_b128 v[150:153], v177 offset:33600
	s_waitcnt lgkmcnt(2)
	v_mfma_f32_16x16x32_bf16 v[80:83], v[138:141], v[68:71], v[126:129]
	v_mfma_f32_16x16x32_bf16 v[138:141], v[138:141], v[100:103], v[122:125]
	v_mfma_f32_16x16x32_bf16 v[112:115], v[142:145], v[130:133], v[80:83]
	v_mfma_f32_16x16x32_bf16 v[80:83], v[142:145], v[134:137], v[138:141]
	s_waitcnt lgkmcnt(0)
	v_mfma_f32_16x16x32_bf16 v[68:71], v[146:149], v[68:71], v[126:129]
	v_mfma_f32_16x16x32_bf16 v[122:125], v[146:149], v[100:103], v[122:125]
	v_mfma_f32_16x16x32_bf16 v[100:103], v[150:153], v[130:133], v[68:71]
	v_mfma_f32_16x16x32_bf16 v[68:71], v[150:153], v[134:137], v[122:125]
	s_cbranch_execz .LBB0_705
	s_branch .LBB0_706

; DEVINL float fexp2(float x) { return __builtin_amdgcn_exp2f(x); }
; #define LDK(DST, KQ) _Pragma("unroll") for (int kc = 0; kc < 4; ++kc) DST[kc] = *(const bf16x8*)(Ks + ((KQ) * 16 + fr) * 136 + kc * 32 + fq * 8)
; DEVINL void attn_item(const Params& p, int item, char* smem, int wv) {
;     ...
;     if (kt * 64 <= qlast) {
;     f32x4 s[2][4];
;     bf16x8 kfa[4], kfb[4];
;     bf16x8 vfa[2], vfb[2];
;     ...
;     LDK(kfa, 0);
;     LDK(kfb, 1); MMS(kfa, 0);
;     LDK(kfa, 2); MMS(kfb, 1);
;     LDK(kfb, 3); MMS(kfa, 2);
;     LDV(vfa, 0); MMS(kfb, 3);
;     bf16x8 pf[2][2];
;     {
;       const unsigned long long msh = mw >> (fq * 4);
;       const int mlo = (int)(unsigned)msh, mhi = (int)(unsigned)(msh >> 32);
;       int mk[4][4];
; #pragma unroll
;       for (int j = 0; j < 4; ++j) {
;         mk[0][j] = __builtin_amdgcn_sbfe(mlo, j, 1); mk[1][j] = __builtin_amdgcn_sbfe(mlo, 16 + j, 1);
;         mk[2][j] = __builtin_amdgcn_sbfe(mhi, j, 1); mk[3][j] = __builtin_amdgcn_sbfe(mhi, 16 + j, 1);
;       }
; #pragma unroll
;       for (int hh = 0; hh < 2; ++hh) {
;         float mx = s[hh][0][0];
; #pragma unroll
;         for (int kq = 0; kq < 4; ++kq)
; #pragma unroll
;           for (int j = 0; j < 4; ++j) mx = fmaxf(mx, s[hh][kq][j]);
;         {
;           auto r1 = __builtin_amdgcn_permlane16_swap(__float_as_uint(mx), __float_as_uint(mx), false, false);
;           mx = fmaxf(__uint_as_float(r1[0]), __uint_as_float(r1[1]));
;           auto r2 = __builtin_amdgcn_permlane32_swap(__float_as_uint(mx), __float_as_uint(mx), false, false);
;           mx = fmaxf(__uint_as_float(r2[0]), __uint_as_float(r2[1]));
;         }
;         if (kt == 0 || __ballot(mx > 8.f)) {
;           const float delta = (kt == 0) ? mx : fmaxf(mx, 0.f);
;           const float alpha = fexp2(-delta);
;           mrun[hh] += delta;
;           lsum[hh] *= alpha;
; #pragma unroll
;           for (int dt = 0; dt < 8; ++dt) o[hh][dt] *= alpha;
; #pragma unroll
;           for (int kq = 0; kq < 4; ++kq)
; #pragma unroll
;             for (int j = 0; j < 4; ++j) s[hh][kq][j] -= delta;
;         }
.LBB0_709:
	s_add_i32 s8, s6, 0xffffffa0
	s_cmp_gt_i32 s8, s1
	s_cbranch_scc1 .LBB0_715
	ds_read_b128 v[116:119], v175
	ds_read_b128 v[120:123], v175 offset:64
	ds_read_b128 v[124:127], v175 offset:128
	ds_read_b128 v[128:131], v175 offset:192
	ds_read_b128 v[132:135], v175 offset:4352
	ds_read_b128 v[140:143], v175 offset:4416
	ds_read_b128 v[144:147], v175 offset:4480
	ds_read_b128 v[178:181], v175 offset:4544
	v_xor_b32_e32 v182, 0x80000000, v3
	v_xor_b32_e32 v186, 0x80000000, v2
	v_mov_b32_e32 v183, v182
	v_mov_b32_e32 v184, v182
	v_mov_b32_e32 v185, v182
	v_mov_b32_e32 v187, v186
	v_mov_b32_e32 v188, v186
	v_mov_b32_e32 v189, v186
	s_waitcnt lgkmcnt(4)
	v_mfma_f32_16x16x32_bf16 v[136:139], v[116:119], v[32:35], v[182:185]
	v_mfma_f32_16x16x32_bf16 v[116:119], v[116:119], v[16:19], v[186:189]
	v_mfma_f32_16x16x32_bf16 v[136:139], v[120:123], v[4:7], v[136:139]
	v_mfma_f32_16x16x32_bf16 v[116:119], v[120:123], v[20:23], v[116:119]
	v_mfma_f32_16x16x32_bf16 v[120:123], v[124:127], v[8:11], v[136:139]
	v_mfma_f32_16x16x32_bf16 v[116:119], v[124:127], v[24:27], v[116:119]
	v_mfma_f32_16x16x32_bf16 v[152:155], v[128:131], v[12:15], v[120:123]
	v_mfma_f32_16x16x32_bf16 v[136:139], v[128:131], v[28:31], v[116:119]
	s_nop 3
	s_nop 1
	ds_read_b128 v[116:119], v175 offset:8704
	ds_read_b128 v[120:123], v175 offset:8768
	ds_read_b128 v[124:127], v175 offset:8832
	ds_read_b128 v[128:131], v175 offset:8896
	s_waitcnt lgkmcnt(4)
	v_mfma_f32_16x16x32_bf16 v[148:151], v[132:135], v[32:35], v[182:185]
	v_mfma_f32_16x16x32_bf16 v[132:135], v[132:135], v[16:19], v[186:189]
	v_mfma_f32_16x16x32_bf16 v[148:151], v[140:143], v[4:7], v[148:151]
	v_mfma_f32_16x16x32_bf16 v[132:135], v[140:143], v[20:23], v[132:135]
	v_mfma_f32_16x16x32_bf16 v[140:143], v[144:147], v[8:11], v[148:151]
	v_mfma_f32_16x16x32_bf16 v[132:135], v[144:147], v[24:27], v[132:135]
	v_mfma_f32_16x16x32_bf16 v[148:151], v[178:181], v[12:15], v[140:143]
	v_mfma_f32_16x16x32_bf16 v[132:135], v[178:181], v[28:31], v[132:135]
	ds_read_b128 v[144:147], v175 offset:13056
	ds_read_b128 v[178:181], v175 offset:13120
	ds_read_b128 v[190:193], v175 offset:13184
	ds_read_b128 v[194:197], v175 offset:13248
	s_waitcnt lgkmcnt(4)
	v_mfma_f32_16x16x32_bf16 v[140:143], v[116:119], v[32:35], v[182:185]
	v_mfma_f32_16x16x32_bf16 v[116:119], v[116:119], v[16:19], v[186:189]
	v_mfma_f32_16x16x32_bf16 v[140:143], v[120:123], v[4:7], v[140:143]
	v_mfma_f32_16x16x32_bf16 v[116:119], v[120:123], v[20:23], v[116:119]
	v_mfma_f32_16x16x32_bf16 v[120:123], v[124:127], v[8:11], v[140:143]
	v_mfma_f32_16x16x32_bf16 v[116:119], v[124:127], v[24:27], v[116:119]
	v_mfma_f32_16x16x32_bf16 v[140:143], v[128:131], v[12:15], v[120:123]
	v_mfma_f32_16x16x32_bf16 v[124:127], v[128:131], v[28:31], v[116:119]
	s_nop 2
	s_nop 0
	s_nop 1
	ds_read_b128 v[116:119], v177 offset:17408
	ds_read_b128 v[120:123], v177 offset:17472
	s_waitcnt lgkmcnt(2)
	v_mfma_f32_16x16x32_bf16 v[128:131], v[144:147], v[32:35], v[182:185]
	v_mfma_f32_16x16x32_bf16 v[144:147], v[144:147], v[16:19], v[186:189]
	v_mfma_f32_16x16x32_bf16 v[128:131], v[178:181], v[4:7], v[128:131]
	v_mfma_f32_16x16x32_bf16 v[144:147], v[178:181], v[20:23], v[144:147]
	v_mfma_f32_16x16x32_bf16 v[128:131], v[190:193], v[8:11], v[128:131]
	v_mfma_f32_16x16x32_bf16 v[178:181], v[190:193], v[24:27], v[144:147]
	v_mfma_f32_16x16x32_bf16 v[144:147], v[194:197], v[12:15], v[128:131]
	v_mfma_f32_16x16x32_bf16 v[128:131], v[194:197], v[28:31], v[178:181]
	s_nop 3
	s_nop 1
	v_max_f32_e32 v179, v152, v152
	v_max_f32_e32 v178, v179, v153
	v_max3_f32 v178, v178, v154, v155
	v_max3_f32 v178, v178, v148, v149
	v_max3_f32 v178, v178, v150, v151
	v_max3_f32 v178, v178, v140, v141
	v_max3_f32 v178, v178, v142, v143
	v_max3_f32 v178, v178, v144, v145
	v_max3_f32 v178, v178, v146, v147
	v_mov_b32_e32 v179, v178
	s_nop 1
	v_permlane16_swap_b32_e32 v178, v179
	v_max_f32_e32 v178, v178, v179
	v_mov_b32_e32 v179, v178
	s_nop 1
	v_permlane32_swap_b32_e32 v178, v179
	v_max_f32_e32 v178, v178, v179
	v_cmp_lt_f32_e32 vcc, s25, v178
	s_cbranch_vccz .LBB0_712
	v_max_f32_e32 v178, 0, v178
	v_exp_f32_e64 v180, -v178
	v_add_f32_e32 v3, v3, v178
	v_pk_add_f32 v[152:153], v[152:153], v[178:179] op_sel_hi:[1,0] neg_lo:[0,1] neg_hi:[0,1]
	v_pk_add_f32 v[154:155], v[154:155], v[178:179] op_sel_hi:[1,0] neg_lo:[0,1] neg_hi:[0,1]
	v_mul_f32_e32 v160, v160, v180
	v_pk_mul_f32 v[90:91], v[90:91], v[180:181] op_sel_hi:[1,0]
	v_pk_mul_f32 v[88:89], v[88:89], v[180:181] op_sel_hi:[1,0]
	v_pk_mul_f32 v[86:87], v[86:87], v[180:181] op_sel_hi:[1,0]
	v_pk_mul_f32 v[84:85], v[84:85], v[180:181] op_sel_hi:[1,0]
	v_pk_mul_f32 v[94:95], v[94:95], v[180:181] op_sel_hi:[1,0]
	v_pk_mul_f32 v[92:93], v[92:93], v[180:181] op_sel_hi:[1,0]
	v_pk_mul_f32 v[98:99], v[98:99], v[180:181] op_sel_hi:[1,0]
	v_pk_mul_f32 v[96:97], v[96:97], v[180:181] op_sel_hi:[1,0]
	v_pk_mul_f32 v[106:107], v[106:107], v[180:181] op_sel_hi:[1,0]
	v_pk_mul_f32 v[104:105], v[104:105], v[180:181] op_sel_hi:[1,0]
	v_pk_mul_f32 v[110:111], v[110:111], v[180:181] op_sel_hi:[1,0]
	v_pk_mul_f32 v[108:109], v[108:109], v[180:181] op_sel_hi:[1,0]
	v_pk_mul_f32 v[114:115], v[114:115], v[180:181] op_sel_hi:[1,0]
	v_pk_mul_f32 v[112:113], v[112:113], v[180:181] op_sel_hi:[1,0]
	v_pk_mul_f32 v[102:103], v[102:103], v[180:181] op_sel_hi:[1,0]
	v_pk_mul_f32 v[100:101], v[100:101], v[180:181] op_sel_hi:[1,0]
	v_pk_add_f32 v[148:149], v[148:149], v[178:179] op_sel_hi:[1,0] neg_lo:[0,1] neg_hi:[0,1]
	v_pk_add_f32 v[150:151], v[150:151], v[178:179] op_sel_hi:[1,0] neg_lo:[0,1] neg_hi:[0,1]
	v_pk_add_f32 v[140:141], v[140:141], v[178:179] op_sel_hi:[1,0] neg_lo:[0,1] neg_hi:[0,1]
	v_pk_add_f32 v[142:143], v[142:143], v[178:179] op_sel_hi:[1,0] neg_lo:[0,1] neg_hi:[0,1]
	v_pk_add_f32 v[144:145], v[144:145], v[178:179] op_sel_hi:[1,0] neg_lo:[0,1] neg_hi:[0,1]
	v_pk_add_f32 v[146:147], v[146:147], v[178:179] op_sel_hi:[1,0] neg_lo:[0,1] neg_hi:[0,1]

; DEVINL float fexp2(float x) { return __builtin_amdgcn_exp2f(x); }
; DEVINL void attn_item(const Params& p, int item, char* smem, int wv) {
;     ...
;       const unsigned long long msh = mw >> (fq * 4);
;       const int mlo = (int)(unsigned)msh, mhi = (int)(unsigned)(msh >> 32);
;       int mk[4][4];
; #pragma unroll
;       for (int j = 0; j < 4; ++j) {
;         mk[0][j] = __builtin_amdgcn_sbfe(mlo, j, 1); mk[1][j] = __builtin_amdgcn_sbfe(mlo, 16 + j, 1);
;         mk[2][j] = __builtin_amdgcn_sbfe(mhi, j, 1); mk[3][j] = __builtin_amdgcn_sbfe(mhi, 16 + j, 1);
;       }
; #pragma unroll
;       for (int hh = 0; hh < 2; ++hh) {
;         float mx = s[hh][0][0];
; #pragma unroll
;         for (int kq = 0; kq < 4; ++kq)
; #pragma unroll
;           for (int j = 0; j < 4; ++j) mx = fmaxf(mx, s[hh][kq][j]);
;         {
;           auto r1 = __builtin_amdgcn_permlane16_swap(__float_as_uint(mx), __float_as_uint(mx), false, false);
;           mx = fmaxf(__uint_as_float(r1[0]), __uint_as_float(r1[1]));
;           auto r2 = __builtin_amdgcn_permlane32_swap(__float_as_uint(mx), __float_as_uint(mx), false, false);
;           mx = fmaxf(__uint_as_float(r2[0]), __uint_as_float(r2[1]));
;         }
;         if (kt == 0 || __ballot(mx > 8.f)) {
;           const float delta = (kt == 0) ? mx : fmaxf(mx, 0.f);
;           const float alpha = fexp2(-delta);
;           mrun[hh] += delta;
;           lsum[hh] *= alpha;
; #pragma unroll
;           for (int dt = 0; dt < 8; ++dt) o[hh][dt] *= alpha;
; #pragma unroll
;           for (int kq = 0; kq < 4; ++kq)
; #pragma unroll
;             for (int j = 0; j < 4; ++j) s[hh][kq][j] -= delta;
;         }
;         float ps = 0.f;
;         float pv[4][4];
; #pragma unroll
;         for (int kq = 0; kq < 4; ++kq)
; #pragma unroll
;           for (int j = 0; j < 4; ++j) {
;             pv[kq][j] = __uint_as_float(__float_as_uint(fexp2(s[hh][kq][j])) & (unsigned)mk[kq][j]);
;             ps += pv[kq][j];
;           }
; #pragma unroll
;         for (int c2 = 0; c2 < 2; ++c2) {
;           u32x4 pw;
;           pw[0] = pk2(pv[2 * c2][0], pv[2 * c2][1]); pw[1] = pk2(pv[2 * c2][2], pv[2 * c2][3]);
;           pw[2] = pk2(pv[2 * c2 + 1][0], pv[2 * c2 + 1][1]); pw[3] = pk2(pv[2 * c2 + 1][2], pv[2 * c2 + 1][3]);
;           pf[hh][c2] = *(bf16x8*)&pw;
;         }
;         lsum[hh] += ps;
.LBB0_714:
	v_exp_f32_e32 v152, v152
	v_exp_f32_e32 v153, v153
	v_lshrrev_b64 v[162:163], v174, v[162:163]
	v_exp_f32_e32 v154, v154
	v_bfe_i32 v178, v162, 0, 1
	v_exp_f32_e32 v155, v155
	v_bfe_i32 v180, v162, 1, 1
	v_and_b32_e32 v152, v178, v152
	v_exp_f32_e32 v148, v148
	v_bfe_i32 v187, v162, 2, 1
	v_and_b32_e32 v153, v180, v153
	v_add_f32_e32 v192, 0, v152
	v_exp_f32_e32 v149, v149
	v_bfe_i32 v186, v162, 3, 1
	v_add_f32_e32 v192, v192, v153
	v_and_b32_e32 v154, v187, v154
	v_exp_f32_e32 v150, v150
	v_exp_f32_e32 v141, v141
	v_bfe_i32 v182, v162, 16, 1
	v_and_b32_e32 v155, v186, v155
	v_add_f32_e32 v192, v192, v154
	v_exp_f32_e32 v151, v151
	v_exp_f32_e32 v140, v140
	v_bfe_i32 v181, v162, 17, 1
	v_add_f32_e32 v192, v192, v155
	v_and_b32_e32 v148, v182, v148
	v_bfe_i32 v183, v163, 1, 1
	v_bfe_i32 v188, v162, 19, 1
	v_bfe_i32 v162, v162, 18, 1
	v_and_b32_e32 v149, v181, v149
	v_add_f32_e32 v192, v192, v148
	v_bfe_i32 v179, v163, 0, 1
	v_add_f32_e32 v192, v192, v149
	v_and_b32_e32 v150, v162, v150
	v_and_b32_e32 v193, v183, v141
	v_exp_f32_e32 v141, v142
	v_and_b32_e32 v151, v188, v151
	v_add_f32_e32 v192, v192, v150
	v_and_b32_e32 v194, v179, v140
	v_exp_f32_e32 v140, v143
	v_add_f32_e32 v192, v192, v151
	v_bfe_i32 v190, v163, 2, 1
	v_add_f32_e32 v142, v192, v194
	v_bfe_i32 v189, v163, 3, 1
	v_add_f32_e32 v142, v142, v193
	v_and_b32_e32 v195, v190, v141
	v_and_b32_e32 v192, v189, v140
	v_add_f32_e32 v140, v142, v195
	v_exp_f32_e32 v141, v144
	v_add_f32_e32 v196, v140, v192
	v_exp_f32_e32 v140, v145
	v_exp_f32_e32 v142, v147
	v_exp_f32_e32 v143, v146
	v_bfe_i32 v185, v163, 16, 1
	v_bfe_i32 v184, v163, 17, 1
	v_bfe_i32 v191, v163, 19, 1
	v_and_b32_e32 v198, v185, v141
	v_exp_f32_e32 v136, v136
	v_bfe_i32 v163, v163, 18, 1
	v_and_b32_e32 v197, v184, v140
	v_and_b32_e32 v199, v191, v142
	v_cvt_pk_bf16_f32 v142, v148, v149
	v_add_f32_e32 v148, v196, v198
	v_exp_f32_e32 v137, v137
	v_and_b32_e32 v200, v163, v143
	v_add_f32_e32 v148, v148, v197
	v_exp_f32_e32 v138, v138
	v_add_f32_e32 v148, v148, v200
	v_exp_f32_e32 v139, v139
	v_add_f32_e32 v148, v148, v199
	v_and_b32_e32 v136, v178, v136
	v_exp_f32_e32 v132, v132
	v_add_f32_e32 v160, v160, v148
	v_and_b32_e32 v137, v180, v137
	v_add_f32_e32 v148, 0, v136
	v_exp_f32_e32 v133, v133
	v_add_f32_e32 v148, v148, v137
	v_and_b32_e32 v138, v187, v138
	v_exp_f32_e32 v134, v134
	v_exp_f32_e32 v125, v125
	v_and_b32_e32 v139, v186, v139
	v_add_f32_e32 v148, v148, v138
	v_exp_f32_e32 v135, v135
	v_exp_f32_e32 v124, v124
	v_add_f32_e32 v148, v148, v139
	v_and_b32_e32 v132, v182, v132
	v_and_b32_e32 v133, v181, v133
	v_add_f32_e32 v148, v148, v132
	v_add_f32_e32 v148, v148, v133
	v_and_b32_e32 v134, v162, v134
	v_and_b32_e32 v149, v183, v125
	v_exp_f32_e32 v125, v126
	v_cvt_pk_bf16_f32 v143, v150, v151
	v_and_b32_e32 v135, v188, v135
	v_add_f32_e32 v148, v148, v134
	v_and_b32_e32 v150, v179, v124
	v_exp_f32_e32 v124, v127
	v_add_f32_e32 v148, v148, v135
	v_add_f32_e32 v126, v148, v150
	v_add_f32_e32 v126, v126, v149
	v_and_b32_e32 v151, v190, v125
	v_and_b32_e32 v148, v189, v124
	v_add_f32_e32 v124, v126, v151
	v_cvt_pk_bf16_f32 v140, v152, v153
	v_add_f32_e32 v152, v124, v148
	v_exp_f32_e32 v124, v129
	v_exp_f32_e32 v125, v128
	v_exp_f32_e32 v126, v131
	v_exp_f32_e32 v127, v130
	v_cvt_pk_bf16_f32 v141, v154, v155
	v_and_b32_e32 v153, v184, v124
	v_and_b32_e32 v154, v185, v125
	v_cvt_pk_bf16_f32 v124, v136, v137
	v_and_b32_e32 v155, v191, v126
	v_and_b32_e32 v162, v163, v127
	v_cvt_pk_bf16_f32 v125, v138, v139
	v_cvt_pk_bf16_f32 v126, v132, v133
	v_cvt_pk_bf16_f32 v127, v134, v135
	v_cvt_pk_bf16_f32 v129, v151, v148
	v_add_f32_e32 v148, v152, v154
	ds_read_b128 v[132:135], v177 offset:19712
	ds_read_b128 v[136:139], v177 offset:19776
	v_add_f32_e32 v148, v148, v153
	v_add_f32_e32 v148, v148, v162
	v_add_f32_e32 v148, v148, v155
	v_add_f32_e32 v161, v161, v148
	v_cvt_pk_bf16_f32 v144, v194, v193
	v_cvt_pk_bf16_f32 v145, v195, v192
	v_cvt_pk_bf16_f32 v146, v198, v197
	v_cvt_pk_bf16_f32 v147, v200, v199
	v_cvt_pk_bf16_f32 v128, v150, v149
	v_cvt_pk_bf16_f32 v130, v154, v153
	v_cvt_pk_bf16_f32 v131, v162, v155
	s_waitcnt lgkmcnt(2)
; #define MMV(SRC, DT) do { __builtin_amdgcn_s_setprio(1); _Pragma("unroll") for (int c2 = 0; c2 < 2; ++c2) { o[0][DT] = mfma16(SRC[c2], pf[0][c2], o[0][DT]); o[1][DT] = mfma16(SRC[c2], pf[1][c2], o[1][DT]); } __builtin_amdgcn_s_setprio(0); } while (0)
; DEVINL void attn_item(const Params& p, int item, char* smem, int wv) {
;     ...
;     LDV(vfb, 1); MMV(vfa, 0);
;     LDV(vfa, 2); MMV(vfb, 1);
;     LDV(vfb, 3); MMV(vfa, 2);
;     LDV(vfa, 4); MMV(vfb, 3);
;     LDV(vfb, 5); MMV(vfa, 4);
;     LDV(vfa, 6); MMV(vfb, 5);
;     LDV(vfb, 7); MMV(vfa, 6);
;     MMV(vfb, 7);
	v_mfma_f32_16x16x32_bf16 v[88:91], v[116:119], v[140:143], v[88:91]
	v_mfma_f32_16x16x32_bf16 v[52:55], v[116:119], v[124:127], v[52:55]
	v_mfma_f32_16x16x32_bf16 v[88:91], v[120:123], v[144:147], v[88:91]
	v_mfma_f32_16x16x32_bf16 v[52:55], v[120:123], v[128:131], v[52:55]
	ds_read_b128 v[116:119], v177 offset:22016
	ds_read_b128 v[120:123], v177 offset:22080
	s_waitcnt lgkmcnt(2)
	v_mfma_f32_16x16x32_bf16 v[84:87], v[132:135], v[140:143], v[84:87]
	v_mfma_f32_16x16x32_bf16 v[56:59], v[132:135], v[124:127], v[56:59]
	v_mfma_f32_16x16x32_bf16 v[84:87], v[136:139], v[144:147], v[84:87]
	v_mfma_f32_16x16x32_bf16 v[56:59], v[136:139], v[128:131], v[56:59]
	ds_read_b128 v[132:135], v177 offset:24320
	ds_read_b128 v[136:139], v177 offset:24384
	s_waitcnt lgkmcnt(2)
	v_mfma_f32_16x16x32_bf16 v[92:95], v[116:119], v[140:143], v[92:95]
	v_mfma_f32_16x16x32_bf16 v[60:63], v[116:119], v[124:127], v[60:63]
	v_mfma_f32_16x16x32_bf16 v[92:95], v[120:123], v[144:147], v[92:95]
	v_mfma_f32_16x16x32_bf16 v[60:63], v[120:123], v[128:131], v[60:63]
	ds_read_b128 v[116:119], v177 offset:26624
	ds_read_b128 v[120:123], v177 offset:26688
	s_waitcnt lgkmcnt(2)
	v_mfma_f32_16x16x32_bf16 v[96:99], v[132:135], v[140:143], v[96:99]
	v_mfma_f32_16x16x32_bf16 v[64:67], v[132:135], v[124:127], v[64:67]
	v_mfma_f32_16x16x32_bf16 v[96:99], v[136:139], v[144:147], v[96:99]
	v_mfma_f32_16x16x32_bf16 v[64:67], v[136:139], v[128:131], v[64:67]
	ds_read_b128 v[132:135], v177 offset:28928
	ds_read_b128 v[136:139], v177 offset:28992
	s_waitcnt lgkmcnt(2)
	v_mfma_f32_16x16x32_bf16 v[104:107], v[116:119], v[140:143], v[104:107]
	v_mfma_f32_16x16x32_bf16 v[72:75], v[116:119], v[124:127], v[72:75]
	v_mfma_f32_16x16x32_bf16 v[104:107], v[120:123], v[144:147], v[104:107]
	v_mfma_f32_16x16x32_bf16 v[72:75], v[120:123], v[128:131], v[72:75]
	ds_read_b128 v[116:119], v177 offset:31232
	ds_read_b128 v[120:123], v177 offset:31296
	s_waitcnt lgkmcnt(2)
	v_mfma_f32_16x16x32_bf16 v[108:111], v[132:135], v[140:143], v[108:111]
	v_mfma_f32_16x16x32_bf16 v[76:79], v[132:135], v[124:127], v[76:79]
	v_mfma_f32_16x16x32_bf16 v[108:111], v[136:139], v[144:147], v[108:111]
	v_mfma_f32_16x16x32_bf16 v[76:79], v[136:139], v[128:131], v[76:79]
	ds_read_b128 v[132:135], v177 offset:33536
	ds_read_b128 v[136:139], v177 offset:33600
	s_waitcnt lgkmcnt(2)
	v_mfma_f32_16x16x32_bf16 v[112:115], v[116:119], v[140:143], v[112:115]
	v_mfma_f32_16x16x32_bf16 v[80:83], v[116:119], v[124:127], v[80:83]
	v_mfma_f32_16x16x32_bf16 v[112:115], v[120:123], v[144:147], v[112:115]
	v_mfma_f32_16x16x32_bf16 v[80:83], v[120:123], v[128:131], v[80:83]
	s_waitcnt lgkmcnt(0)
	v_mfma_f32_16x16x32_bf16 v[100:103], v[132:135], v[140:143], v[100:103]
	v_mfma_f32_16x16x32_bf16 v[68:71], v[132:135], v[124:127], v[68:71]
	v_mfma_f32_16x16x32_bf16 v[100:103], v[136:139], v[144:147], v[100:103]
	v_mfma_f32_16x16x32_bf16 v[68:71], v[136:139], v[128:131], v[68:71]

; #define LDK(DST, KQ) _Pragma("unroll") for (int kc = 0; kc < 4; ++kc) DST[kc] = *(const bf16x8*)(Ks + ((KQ) * 16 + fr) * 136 + kc * 32 + fq * 8)
; DEVINL void attn_item(const Params& p, int item, char* smem, int wv) {
;     ...
;   const size_t qtok = (size_t)b * SEQ + q0 + wid * 16 + fr;
;   bf16x8 qf[2][4];
; #pragma unroll
;   for (int hh = 0; hh < 2; ++hh)
; #pragma unroll
;     for (int kc = 0; kc < 4; ++kc)
;       qf[hh][kc] = *(const bf16x8*)(hb + qtok * HS + 2560 + (kvh * 2 + hh) * 128 + kc * 32 + fq * 8);
;   f32x4 o[2][8];
; #pragma unroll
;   for (int hh = 0; hh < 2; ++hh)
; #pragma unroll
;     for (int dt = 0; dt < 8; ++dt) o[hh][dt] = f32x4{0.f, 0.f, 0.f, 0.f};
;   float mrun[2] = {0.f, 0.f}, lsum[2] = {0.f, 0.f};
;   unsigned long long mw_next = bits[qtok * 64];
;   u32x4 rk[2], rv[2];
;   const u16* kg = hb + ((size_t)b * SEQ + (tid >> 4)) * HS + 3584 + kvh * 128 + (tid & 15) * 8;
;   const u16* vg = vT + ((size_t)(b * 4 + kvh) * 128 + (tid >> 3)) * SEQ + (tid & 7) * 8;
; #pragma unroll
;   for (int i = 0; i < 2; ++i) {
;     rk[i] = *(const u32x4*)(kg + (size_t)(32 * i) * HS);
;     rv[i] = *(const u32x4*)(vg + (size_t)(64 * i) * SEQ);
;   }
;   for (int kt = 0; kt < ntile; ++kt) {
; #pragma unroll
;     for (int i = 0; i < 2; ++i) {
;       *(u32x4*)(Ks + ((tid >> 4) + 32 * i) * 136 + (tid & 15) * 8) = rk[i];
;       *(u32x4*)(Vs + ((tid >> 3) + 64 * i) * 72 + (tid & 7) * 8) = rv[i];
;     }
;     __syncthreads();
;     if (kt + 1 < ntile) {
; #pragma unroll
;       for (int i = 0; i < 2; ++i) {
;         rk[i] = *(const u32x4*)(kg + (size_t)((kt + 1) * 64 + 32 * i) * HS);
;         rv[i] = *(const u32x4*)(vg + (size_t)(64 * i) * SEQ + (kt + 1) * 64);
;       }
;     }
;     const unsigned long long mw = mw_next;
;     if (kt + 1 < ntile) mw_next = bits[qtok * 64 + kt + 1];
;     if (kt * 64 <= qlast) {
;     f32x4 s[2][4];
;     bf16x8 kfa[4], kfb[4];
;     bf16x8 vfa[2], vfb[2];
;     ...
;     LDK(kfa, 0);
;     LDK(kfb, 1); MMS(kfa, 0);
;     LDK(kfa, 2); MMS(kfb, 1);
;     LDK(kfb, 3); MMS(kfa, 2);
;     LDV(vfa, 0); MMS(kfb, 3);
.Lprio_skip_a1:
	s_and_b32 s34, s3, 0x3000
	v_and_b32_e32 v60, 15, v120
	s_and_b32 s2, s7, -16
	s_add_i32 s10, s6, s34
	s_ashr_i32 s3, s2, 31
	v_or_b32_e32 v0, s10, v60
	v_lshl_add_u64 v[156:157], v[0:1], 0, s[2:3]
	v_mov_b64_e32 v[2:3], s[62:63]
	v_mad_u64_u32 v[4:5], s[2:3], v156, s22, v[2:3]
	s_and_b32 s5, s1, 3
	v_mad_i32_i24 v5, v157, s22, v5
	v_and_b32_e32 v0, 48, v120
	v_lshl_add_u64 v[4:5], v[4:5], 0, v[0:1]
	s_lshl_b32 s10, s5, 9
	v_ashrrev_i32_e32 v14, 4, v120
	v_lshl_add_u64 v[8:9], v[4:5], 0, s[10:11]
	v_add_u32_e32 v4, s34, v14
	s_lshl_b32 s18, s5, 8
	s_mov_b32 s19, s11
	v_mad_i64_i32 v[2:3], s[2:3], v4, s22, v[2:3]
	v_lshlrev_b32_e32 v6, 4, v120
	v_lshl_add_u64 v[2:3], v[2:3], 0, s[18:19]
	v_and_b32_e32 v10, 0xf0, v6
	v_mov_b32_e32 v11, v1
	v_lshl_add_u64 v[116:117], v[2:3], 0, v[10:11]
	s_lshl_b32 s1, s1, 7
	v_ashrrev_i32_e32 v2, 3, v120
	s_and_b32 s10, s1, 0x780
	v_ashrrev_i32_e32 v3, 31, v2
	v_lshl_add_u64 v[4:5], v[2:3], 0, s[10:11]
	v_lshlrev_b64 v[4:5], 13, v[4:5]
	v_lshl_add_u64 v[4:5], s[40:41], 0, v[4:5]
	v_and_b32_e32 v12, 0x70, v6
	v_mov_b32_e32 v13, v1
	v_lshl_add_u64 v[158:159], v[4:5], 0, v[12:13]
	v_add_co_u32_e32 v4, vcc, s23, v116
	global_load_dwordx4 v[36:39], v[158:159], off
	s_nop 0
	v_addc_co_u32_e32 v5, vcc, 0, v117, vcc
	v_add_co_u32_e32 v6, vcc, s24, v116
	v_mul_lo_u32 v2, v2, s27
	s_nop 0
	v_addc_co_u32_e32 v7, vcc, 0, v117, vcc
	global_load_dwordx4 v[40:43], v[4:5], off offset:3072
	global_load_dwordx4 v[44:47], v[6:7], off offset:3072
	v_add_co_u32_e32 v52, vcc, s25, v158
	v_add_u32_e32 v11, 0, v12
	s_nop 0
	v_addc_co_u32_e32 v53, vcc, 0, v159, vcc
	global_load_dwordx4 v[48:51], v[52:53], off
	v_mul_lo_u32 v3, v14, s26
	v_add_u32_e32 v10, 0, v10
	v_and_b32_e32 v173, 64, v12
	v_bfe_u32 v11, v12, 4, 1
	v_lshl_or_b32 v173, v11, 5, v173
	v_bfe_u32 v11, v12, 5, 1
	v_lshl_or_b32 v173, v11, 3, v173
	v_add_u32_e32 v173, v173, v2
	v_add_co_u32_e64 v2, s[2:3], s23, v8
	v_lshl_add_u64 v[28:29], v[8:9], 0, s[12:13]
	v_add_u32_e32 v172, v10, v3
	v_lshlrev_b64 v[118:119], 9, v[156:157]
	v_add_co_u32_e32 v54, vcc, 0xa1000, v116
	v_addc_co_u32_e64 v3, s[2:3], 0, v9, s[2:3]
	global_load_dwordx4 v[4:7], v[28:29], off offset:64
	v_lshl_add_u64 v[56:57], s[38:39], 0, v[118:119]
	v_addc_co_u32_e32 v55, vcc, 0, v117, vcc
	global_load_dwordx4 v[8:11], v[28:29], off offset:128
	global_load_dwordx4 v[12:15], v[28:29], off offset:192
	global_load_dwordx4 v[16:19], v[28:29], off offset:256
	global_load_dwordx4 v[20:23], v[28:29], off offset:320
	global_load_dwordx4 v[24:27], v[28:29], off offset:384
	s_nop 0
	global_load_dwordx4 v[28:31], v[28:29], off offset:448
	s_nop 0
	global_load_dwordx4 v[32:35], v[2:3], off offset:1024
	s_nop 0
	global_load_dwordx2 v[2:3], v[56:57], off
	v_add_co_u32_e32 v58, vcc, 0xf1000, v116
	s_add_i32 s1, s7, s6
	s_nop 0
	v_addc_co_u32_e32 v59, vcc, 0, v117, vcc
	s_cmp_gt_i32 s1, -1
	s_mov_b64 s[2:3], -1
	s_waitcnt vmcnt(11)
	ds_write_b128 v172, v[40:43]
	ds_write_b64 v173, v[36:37] offset:17408
	ds_write_b64 v173, v[38:39] offset:17424
	s_waitcnt vmcnt(10)
	ds_write_b128 v172, v[44:47] offset:8704
	s_waitcnt vmcnt(9)
	ds_write_b64 v173, v[48:49] offset:26624
	ds_write_b64 v173, v[50:51] offset:26640
	s_waitcnt lgkmcnt(0)
	s_barrier
	global_load_dwordx4 v[44:47], v[58:59], off offset:3072
	global_load_dwordx4 v[36:39], v[54:55], off offset:3072
	global_load_dwordx4 v[48:51], v[52:53], off offset:128
	global_load_dwordx4 v[40:43], v[158:159], off offset:128
	global_load_dwordx2 v[162:163], v[56:57], off offset:8
	v_mad_u32_u24 v52, v60, s26, 0
	v_lshlrev_b32_e32 v53, 7, v60
	v_lshrrev_b32_e32 v54, 2, v120
	v_sub_u32_e32 v53, v52, v53
	v_and_b32_e32 v174, 12, v54
	v_add_u32_e32 v175, v52, v0
	v_lshl_add_u32 v177, v174, 2, v53
	s_cbranch_scc0 .LBB0_1726
	ds_read_b128 v[52:55], v175
	ds_read_b128 v[56:59], v175 offset:64
	ds_read_b128 v[60:63], v175 offset:128
	ds_read_b128 v[64:67], v175 offset:192
	ds_read_b128 v[68:71], v175 offset:4352
	ds_read_b128 v[72:75], v175 offset:4416
	ds_read_b128 v[76:79], v175 offset:4480
	ds_read_b128 v[80:83], v175 offset:4544
	s_mov_b32 s6, s4
	s_mov_b32 s7, s4
	s_mov_b32 s5, s4
	v_mov_b64_e32 v[86:87], s[6:7]
	v_mov_b64_e32 v[84:85], s[4:5]
	s_waitcnt vmcnt(6) lgkmcnt(7)
	s_nop 0
	v_mfma_f32_16x16x32_bf16 v[88:91], v[52:55], v[32:35], v[84:87]
	v_mfma_f32_16x16x32_bf16 v[52:55], v[52:55], v[16:19], v[84:87]
	s_waitcnt lgkmcnt(4)
	v_mfma_f32_16x16x32_bf16 v[88:91], v[56:59], v[4:7], v[88:91]
	v_mfma_f32_16x16x32_bf16 v[52:55], v[56:59], v[20:23], v[52:55]
	v_mfma_f32_16x16x32_bf16 v[56:59], v[60:63], v[8:11], v[88:91]
	v_mfma_f32_16x16x32_bf16 v[52:55], v[60:63], v[24:27], v[52:55]
	v_mfma_f32_16x16x32_bf16 v[60:63], v[64:67], v[12:15], v[56:59]
	v_mfma_f32_16x16x32_bf16 v[64:67], v[64:67], v[28:31], v[52:55]
	s_nop 3
	s_nop 1
	ds_read_b128 v[52:55], v175 offset:8704
	ds_read_b128 v[56:59], v175 offset:8768
	ds_read_b128 v[88:91], v175 offset:8832
	ds_read_b128 v[92:95], v175 offset:8896
	s_waitcnt lgkmcnt(4)
	v_mfma_f32_16x16x32_bf16 v[96:99], v[68:71], v[32:35], v[84:87]
	v_mfma_f32_16x16x32_bf16 v[68:71], v[68:71], v[16:19], v[84:87]
	v_mfma_f32_16x16x32_bf16 v[96:99], v[72:75], v[4:7], v[96:99]
	v_mfma_f32_16x16x32_bf16 v[68:71], v[72:75], v[20:23], v[68:71]
	v_mfma_f32_16x16x32_bf16 v[72:75], v[76:79], v[8:11], v[96:99]
	v_mfma_f32_16x16x32_bf16 v[68:71], v[76:79], v[24:27], v[68:71]
	v_mfma_f32_16x16x32_bf16 v[72:75], v[80:83], v[12:15], v[72:75]
	v_mfma_f32_16x16x32_bf16 v[68:71], v[80:83], v[28:31], v[68:71]
	ds_read_b128 v[76:79], v175 offset:13056
	ds_read_b128 v[80:83], v175 offset:13120
	s_nop 0
	ds_read_b128 v[96:99], v175 offset:13184
	ds_read_b128 v[100:103], v175 offset:13248
	s_waitcnt lgkmcnt(4)
; DEVINL float fexp2(float x) { return __builtin_amdgcn_exp2f(x); }
; #define LDK(DST, KQ) _Pragma("unroll") for (int kc = 0; kc < 4; ++kc) DST[kc] = *(const bf16x8*)(Ks + ((KQ) * 16 + fr) * 136 + kc * 32 + fq * 8)
; DEVINL void attn_item(const Params& p, int item, char* smem, int wv) {
;     ...
;     LDK(kfb, 1); MMS(kfa, 0);
;     LDK(kfa, 2); MMS(kfb, 1);
;     LDK(kfb, 3); MMS(kfa, 2);
;     LDV(vfa, 0); MMS(kfb, 3);
;     bf16x8 pf[2][2];
;     {
;       const unsigned long long msh = mw >> (fq * 4);
;       const int mlo = (int)(unsigned)msh, mhi = (int)(unsigned)(msh >> 32);
;       int mk[4][4];
; #pragma unroll
;       for (int j = 0; j < 4; ++j) {
;         mk[0][j] = __builtin_amdgcn_sbfe(mlo, j, 1); mk[1][j] = __builtin_amdgcn_sbfe(mlo, 16 + j, 1);
;         mk[2][j] = __builtin_amdgcn_sbfe(mhi, j, 1); mk[3][j] = __builtin_amdgcn_sbfe(mhi, 16 + j, 1);
;       }
; #pragma unroll
;       for (int hh = 0; hh < 2; ++hh) {
;         float mx = s[hh][0][0];
; #pragma unroll
;         for (int kq = 0; kq < 4; ++kq)
; #pragma unroll
;           for (int j = 0; j < 4; ++j) mx = fmaxf(mx, s[hh][kq][j]);
;         {
;           auto r1 = __builtin_amdgcn_permlane16_swap(__float_as_uint(mx), __float_as_uint(mx), false, false);
;           mx = fmaxf(__uint_as_float(r1[0]), __uint_as_float(r1[1]));
;           auto r2 = __builtin_amdgcn_permlane32_swap(__float_as_uint(mx), __float_as_uint(mx), false, false);
;           mx = fmaxf(__uint_as_float(r2[0]), __uint_as_float(r2[1]));
;         }
;         if (kt == 0 || __ballot(mx > 8.f)) {
;           const float delta = (kt == 0) ? mx : fmaxf(mx, 0.f);
;           const float alpha = fexp2(-delta);
;           mrun[hh] += delta;
;           lsum[hh] *= alpha;
; #pragma unroll
;           for (int dt = 0; dt < 8; ++dt) o[hh][dt] *= alpha;
; #pragma unroll
;           for (int kq = 0; kq < 4; ++kq)
; #pragma unroll
;             for (int j = 0; j < 4; ++j) s[hh][kq][j] -= delta;
;         }
;         float ps = 0.f;
;         float pv[4][4];
; #pragma unroll
;         for (int kq = 0; kq < 4; ++kq)
; #pragma unroll
;           for (int j = 0; j < 4; ++j) {
;             pv[kq][j] = __uint_as_float(__float_as_uint(fexp2(s[hh][kq][j])) & (unsigned)mk[kq][j]);
;             ps += pv[kq][j];
;           }
	v_mfma_f32_16x16x32_bf16 v[104:107], v[52:55], v[32:35], v[84:87]
	v_mfma_f32_16x16x32_bf16 v[52:55], v[52:55], v[16:19], v[84:87]
	v_mfma_f32_16x16x32_bf16 v[104:107], v[56:59], v[4:7], v[104:107]
	v_mfma_f32_16x16x32_bf16 v[52:55], v[56:59], v[20:23], v[52:55]
	v_mfma_f32_16x16x32_bf16 v[56:59], v[88:91], v[8:11], v[104:107]
	v_mfma_f32_16x16x32_bf16 v[52:55], v[88:91], v[24:27], v[52:55]
	v_mfma_f32_16x16x32_bf16 v[88:91], v[92:95], v[12:15], v[56:59]
	v_mfma_f32_16x16x32_bf16 v[92:95], v[92:95], v[28:31], v[52:55]
	s_nop 2
	s_nop 0
	s_nop 1
	ds_read_b128 v[52:55], v177 offset:17408
	ds_read_b128 v[56:59], v177 offset:17472
	s_waitcnt lgkmcnt(2)
	v_mfma_f32_16x16x32_bf16 v[104:107], v[76:79], v[32:35], v[84:87]
	v_mfma_f32_16x16x32_bf16 v[76:79], v[76:79], v[16:19], v[84:87]
	v_mfma_f32_16x16x32_bf16 v[84:87], v[80:83], v[4:7], v[104:107]
	v_mfma_f32_16x16x32_bf16 v[76:79], v[80:83], v[20:23], v[76:79]
	v_mfma_f32_16x16x32_bf16 v[80:83], v[96:99], v[8:11], v[84:87]
	v_mfma_f32_16x16x32_bf16 v[76:79], v[96:99], v[24:27], v[76:79]
	v_mfma_f32_16x16x32_bf16 v[80:83], v[100:103], v[12:15], v[80:83]
	v_mfma_f32_16x16x32_bf16 v[76:79], v[100:103], v[28:31], v[76:79]
	s_waitcnt vmcnt(5)
	v_lshrrev_b64 v[2:3], v174, v[2:3]
	v_bfe_i32 v0, v2, 0, 1
	v_bfe_i32 v86, v2, 16, 1
	v_bfe_i32 v87, v3, 0, 1
	v_bfe_i32 v96, v3, 16, 1
	v_bfe_i32 v97, v2, 1, 1
	v_bfe_i32 v98, v2, 17, 1
	v_bfe_i32 v99, v3, 1, 1
	v_bfe_i32 v104, v3, 17, 1
	v_bfe_i32 v100, v2, 2, 1
	v_bfe_i32 v101, v2, 18, 1
	v_bfe_i32 v105, v3, 2, 1
	v_bfe_i32 v106, v3, 18, 1
	v_bfe_i32 v102, v2, 3, 1
	v_bfe_i32 v103, v2, 19, 1
	v_bfe_i32 v107, v3, 3, 1
	v_bfe_i32 v108, v3, 19, 1
	v_max_f32_e32 v3, v60, v60
	v_max_f32_e32 v2, v3, v61
	v_max3_f32 v2, v2, v62, v63
	v_max3_f32 v2, v2, v72, v73
	v_max3_f32 v2, v2, v74, v75
	v_max3_f32 v2, v2, v88, v89
	v_max3_f32 v2, v2, v90, v91
	v_max3_f32 v2, v2, v80, v81
	v_max3_f32 v2, v2, v82, v83
	v_mov_b32_e32 v3, v2
	s_nop 1
	v_permlane16_swap_b32_e32 v2, v3
	v_max_f32_e32 v2, v2, v3
	v_mov_b32_e32 v3, v2
	s_nop 1
	v_permlane32_swap_b32_e32 v2, v3
	v_max_f32_e32 v3, v2, v3
	v_sub_f32_e32 v2, v80, v3
	v_sub_f32_e32 v61, v61, v3
	v_sub_f32_e32 v80, v81, v3
	v_sub_f32_e32 v81, v82, v3
	v_sub_f32_e32 v82, v83, v3
	v_sub_f32_e32 v83, v88, v3
	v_sub_f32_e32 v88, v90, v3
	v_exp_f32_e32 v90, v61
	v_exp_f32_e32 v115, v2
	v_max_f32_e32 v61, v64, v64
	v_max_f32_e32 v2, v61, v65
	v_max3_f32 v2, v2, v66, v67
	v_max3_f32 v2, v2, v68, v69
	v_max3_f32 v2, v2, v70, v71
	v_max3_f32 v2, v2, v92, v93
	v_max3_f32 v2, v2, v94, v95
	v_max3_f32 v2, v2, v76, v77
	v_max3_f32 v2, v2, v78, v79
	v_mov_b32_e32 v61, v2
	s_nop 1
	v_permlane16_swap_b32_e32 v2, v61
	v_max_f32_e32 v2, v2, v61
	v_mov_b32_e32 v61, v2
	s_nop 1
	v_permlane32_swap_b32_e32 v2, v61
	v_max_f32_e32 v2, v2, v61
	v_sub_f32_e32 v60, v60, v3
	v_sub_f32_e32 v64, v64, v2
	v_exp_f32_e32 v60, v60
	v_sub_f32_e32 v65, v65, v2
	v_exp_f32_e32 v64, v64
	v_sub_f32_e32 v62, v62, v3
	v_sub_f32_e32 v66, v66, v2
	v_exp_f32_e32 v65, v65
	v_sub_f32_e32 v85, v89, v3
	v_sub_f32_e32 v89, v91, v3
	v_sub_f32_e32 v63, v63, v3
	v_exp_f32_e32 v91, v62
	v_sub_f32_e32 v67, v67, v2
	v_exp_f32_e32 v66, v66
	v_sub_f32_e32 v72, v72, v3
	v_exp_f32_e32 v109, v63
	v_sub_f32_e32 v61, v68, v2
	v_sub_f32_e32 v62, v69, v2
	v_exp_f32_e32 v67, v67
	v_sub_f32_e32 v73, v73, v3
	v_exp_f32_e32 v72, v72
	v_exp_f32_e32 v113, v83
	v_exp_f32_e32 v125, v82
	v_sub_f32_e32 v82, v92, v2
	v_sub_f32_e32 v83, v93, v2
	v_sub_f32_e32 v63, v70, v2
	v_sub_f32_e32 v68, v71, v2
	v_exp_f32_e32 v70, v61
	v_exp_f32_e32 v71, v62
	v_and_b32_e32 v61, v0, v64
	v_and_b32_e32 v60, v0, v60
	v_and_b32_e32 v62, v97, v90
	v_sub_f32_e32 v74, v74, v3
	v_exp_f32_e32 v110, v73
	v_exp_f32_e32 v121, v80
	v_exp_f32_e32 v124, v81
	v_sub_f32_e32 v122, v76, v2
	v_sub_f32_e32 v126, v78, v2
	v_exp_f32_e32 v76, v63
	v_exp_f32_e32 v78, v68
	v_and_b32_e32 v63, v97, v65
	v_cvt_pk_bf16_f32 v68, v60, v62
	v_pk_add_f32 v[80:81], v[60:61], 0 op_sel_hi:[1,0]
	v_exp_f32_e32 v0, v82
	v_exp_f32_e32 v60, v83
	v_sub_f32_e32 v75, v75, v3
	v_exp_f32_e32 v111, v74
	v_and_b32_e32 v65, v100, v66
	v_and_b32_e32 v64, v100, v91
	v_pk_add_f32 v[80:81], v[80:81], v[62:63]
	v_exp_f32_e32 v112, v75
	v_and_b32_e32 v67, v102, v67
	v_and_b32_e32 v66, v102, v109
	v_pk_add_f32 v[80:81], v[80:81], v[64:65]
	v_sub_f32_e32 v93, v95, v2
	v_and_b32_e32 v73, v86, v70
	v_and_b32_e32 v72, v86, v72
	v_pk_add_f32 v[80:81], v[80:81], v[66:67]
	v_exp_f32_e32 v114, v85
	v_sub_f32_e32 v92, v94, v2
	v_and_b32_e32 v75, v98, v71
	v_and_b32_e32 v74, v98, v110
	v_pk_add_f32 v[80:81], v[80:81], v[72:73]
	v_and_b32_e32 v83, v87, v0
	v_and_b32_e32 v82, v87, v113
	v_and_b32_e32 v87, v99, v60
	v_exp_f32_e32 v60, v93
	v_exp_f32_e32 v88, v88
	v_sub_f32_e32 v123, v77, v2
	v_and_b32_e32 v77, v101, v76
	v_and_b32_e32 v76, v101, v111
	v_pk_add_f32 v[80:81], v[80:81], v[74:75]
	v_exp_f32_e32 v0, v92
	v_exp_f32_e32 v89, v89
	v_sub_f32_e32 v127, v79, v2
	v_and_b32_e32 v79, v103, v78
	v_and_b32_e32 v78, v103, v112
	v_pk_add_f32 v[80:81], v[80:81], v[76:77]
	v_exp_f32_e32 v62, v122
	v_pk_add_f32 v[80:81], v[80:81], v[78:79]
	v_cvt_pk_bf16_f32 v69, v64, v66
	v_and_b32_e32 v86, v99, v114
	v_exp_f32_e32 v64, v123
	v_cvt_pk_bf16_f32 v100, v61, v63
	v_cvt_pk_bf16_f32 v102, v73, v75
	v_and_b32_e32 v75, v107, v60
	v_pk_add_f32 v[60:61], v[80:81], v[82:83]
	v_cvt_pk_bf16_f32 v70, v72, v74
	v_exp_f32_e32 v66, v126
	v_and_b32_e32 v73, v105, v0
	v_and_b32_e32 v72, v105, v88
	v_pk_add_f32 v[60:61], v[60:61], v[86:87]
	v_exp_f32_e32 v90, v127
	v_and_b32_e32 v74, v107, v89
	v_pk_add_f32 v[60:61], v[60:61], v[72:73]
	v_cvt_pk_bf16_f32 v71, v76, v78
	v_cvt_pk_bf16_f32 v103, v77, v79
	v_and_b32_e32 v77, v96, v62
	v_and_b32_e32 v76, v96, v115
	v_pk_add_f32 v[60:61], v[60:61], v[74:75]
	v_and_b32_e32 v79, v104, v64
	v_and_b32_e32 v78, v104, v121
	v_pk_add_f32 v[60:61], v[60:61], v[76:77]
	v_and_b32_e32 v89, v106, v66
	v_and_b32_e32 v88, v106, v124
	v_pk_add_f32 v[60:61], v[60:61], v[78:79]
	v_and_b32_e32 v91, v108, v90
	v_and_b32_e32 v90, v108, v125
	v_pk_add_f32 v[60:61], v[60:61], v[88:89]
	v_exp_f32_e64 v84, -v3
	v_exp_f32_e64 v85, -v2
	v_cvt_pk_bf16_f32 v101, v65, v67
	v_pk_add_f32 v[80:81], v[60:61], v[90:91]
	ds_read_b128 v[60:63], v177 offset:19712
	ds_read_b128 v[64:67], v177 offset:19776
	v_pk_add_f32 v[2:3], v[2:3], 0 op_sel_hi:[1,0]
	v_pk_mul_f32 v[122:123], v[84:85], 0 op_sel_hi:[1,0]
	v_pk_fma_f32 v[160:161], v[84:85], 0, v[80:81] op_sel_hi:[1,0,1]
	v_mov_b32_e32 v126, v122
	v_mov_b32_e32 v127, v122
	v_mov_b32_e32 v128, v122
	v_mov_b32_e32 v129, v122
	v_cvt_pk_bf16_f32 v130, v82, v86
	v_cvt_pk_bf16_f32 v131, v72, v74
	v_cvt_pk_bf16_f32 v132, v76, v78
	v_cvt_pk_bf16_f32 v133, v88, v90
	v_mov_b32_e32 v122, v123
	v_mov_b32_e32 v124, v123
	v_mov_b32_e32 v125, v123
	v_cvt_pk_bf16_f32 v134, v83, v87
	v_cvt_pk_bf16_f32 v135, v73, v75
	v_cvt_pk_bf16_f32 v136, v77, v79
	v_cvt_pk_bf16_f32 v137, v89, v91
	s_waitcnt lgkmcnt(2)
; #define MMV(SRC, DT) do { __builtin_amdgcn_s_setprio(1); _Pragma("unroll") for (int c2 = 0; c2 < 2; ++c2) { o[0][DT] = mfma16(SRC[c2], pf[0][c2], o[0][DT]); o[1][DT] = mfma16(SRC[c2], pf[1][c2], o[1][DT]); } __builtin_amdgcn_s_setprio(0); } while (0)
; DEVINL void attn_item(const Params& p, int item, char* smem, int wv) {
;     ...
;     LDV(vfb, 1); MMV(vfa, 0);
;     LDV(vfa, 2); MMV(vfb, 1);
;     LDV(vfb, 3); MMV(vfa, 2);
;     LDV(vfa, 4); MMV(vfb, 3);
;     LDV(vfb, 5); MMV(vfa, 4);
;     LDV(vfa, 6); MMV(vfb, 5);
;     LDV(vfb, 7); MMV(vfa, 6);
;     MMV(vfb, 7);
	v_mfma_f32_16x16x32_bf16 v[72:75], v[52:55], v[68:71], v[126:129]
	v_mfma_f32_16x16x32_bf16 v[52:55], v[52:55], v[100:103], v[122:125]
	v_mfma_f32_16x16x32_bf16 v[88:91], v[56:59], v[130:133], v[72:75]
	v_mfma_f32_16x16x32_bf16 v[52:55], v[56:59], v[134:137], v[52:55]
	s_nop 1
	s_nop 2
	ds_read_b128 v[72:75], v177 offset:22016
	ds_read_b128 v[76:79], v177 offset:22080
	s_waitcnt lgkmcnt(2)
	v_mfma_f32_16x16x32_bf16 v[56:59], v[60:63], v[68:71], v[126:129]
	v_mfma_f32_16x16x32_bf16 v[60:63], v[60:63], v[100:103], v[122:125]
	v_mfma_f32_16x16x32_bf16 v[84:87], v[64:67], v[130:133], v[56:59]
	v_mfma_f32_16x16x32_bf16 v[56:59], v[64:67], v[134:137], v[60:63]
	ds_read_b128 v[64:67], v177 offset:24320
	ds_read_b128 v[80:83], v177 offset:24384
	s_waitcnt lgkmcnt(2)
	v_mfma_f32_16x16x32_bf16 v[60:63], v[72:75], v[68:71], v[126:129]
	v_mfma_f32_16x16x32_bf16 v[72:75], v[72:75], v[100:103], v[122:125]
	v_mfma_f32_16x16x32_bf16 v[92:95], v[76:79], v[130:133], v[60:63]
	v_mfma_f32_16x16x32_bf16 v[60:63], v[76:79], v[134:137], v[72:75]
	s_nop 2
	s_nop 2
	ds_read_b128 v[72:75], v177 offset:26624
	ds_read_b128 v[76:79], v177 offset:26688
	s_waitcnt lgkmcnt(2)
	v_mfma_f32_16x16x32_bf16 v[96:99], v[64:67], v[68:71], v[126:129]
	v_mfma_f32_16x16x32_bf16 v[64:67], v[64:67], v[100:103], v[122:125]
	v_mfma_f32_16x16x32_bf16 v[96:99], v[80:83], v[130:133], v[96:99]
	v_mfma_f32_16x16x32_bf16 v[64:67], v[80:83], v[134:137], v[64:67]
	ds_read_b128 v[80:83], v177 offset:28928
	ds_read_b128 v[112:115], v177 offset:28992
	s_waitcnt lgkmcnt(2)
	v_mfma_f32_16x16x32_bf16 v[104:107], v[72:75], v[68:71], v[126:129]
	v_mfma_f32_16x16x32_bf16 v[72:75], v[72:75], v[100:103], v[122:125]
	v_mfma_f32_16x16x32_bf16 v[104:107], v[76:79], v[130:133], v[104:107]
	v_mfma_f32_16x16x32_bf16 v[72:75], v[76:79], v[134:137], v[72:75]
	ds_read_b128 v[138:141], v177 offset:31232
	ds_read_b128 v[142:145], v177 offset:31296
	s_waitcnt lgkmcnt(2)
	v_mfma_f32_16x16x32_bf16 v[76:79], v[80:83], v[68:71], v[126:129]
	v_mfma_f32_16x16x32_bf16 v[80:83], v[80:83], v[100:103], v[122:125]
	v_mfma_f32_16x16x32_bf16 v[108:111], v[112:115], v[130:133], v[76:79]
	v_mfma_f32_16x16x32_bf16 v[76:79], v[112:115], v[134:137], v[80:83]
	ds_read_b128 v[146:149], v177 offset:33536
	ds_read_b128 v[150:153], v177 offset:33600
	s_waitcnt lgkmcnt(2)
	v_mfma_f32_16x16x32_bf16 v[80:83], v[138:141], v[68:71], v[126:129]
	v_mfma_f32_16x16x32_bf16 v[138:141], v[138:141], v[100:103], v[122:125]
	v_mfma_f32_16x16x32_bf16 v[112:115], v[142:145], v[130:133], v[80:83]
	v_mfma_f32_16x16x32_bf16 v[80:83], v[142:145], v[134:137], v[138:141]
	s_waitcnt lgkmcnt(0)
	v_mfma_f32_16x16x32_bf16 v[68:71], v[146:149], v[68:71], v[126:129]
	v_mfma_f32_16x16x32_bf16 v[122:125], v[146:149], v[100:103], v[122:125]
	v_mfma_f32_16x16x32_bf16 v[100:103], v[150:153], v[130:133], v[68:71]
	v_mfma_f32_16x16x32_bf16 v[68:71], v[150:153], v[134:137], v[122:125]
	s_cbranch_execz .LBB0_1727
	s_branch .LBB0_1728

; DEVINL float fexp2(float x) { return __builtin_amdgcn_exp2f(x); }
; #define LDK(DST, KQ) _Pragma("unroll") for (int kc = 0; kc < 4; ++kc) DST[kc] = *(const bf16x8*)(Ks + ((KQ) * 16 + fr) * 136 + kc * 32 + fq * 8)
; DEVINL void attn_item(const Params& p, int item, char* smem, int wv) {
;     ...
;     if (kt * 64 <= qlast) {
;     f32x4 s[2][4];
;     bf16x8 kfa[4], kfb[4];
;     bf16x8 vfa[2], vfb[2];
;     ...
;     LDK(kfa, 0);
;     LDK(kfb, 1); MMS(kfa, 0);
;     LDK(kfa, 2); MMS(kfb, 1);
;     LDK(kfb, 3); MMS(kfa, 2);
;     LDV(vfa, 0); MMS(kfb, 3);
;     bf16x8 pf[2][2];
;     {
;       const unsigned long long msh = mw >> (fq * 4);
;       const int mlo = (int)(unsigned)msh, mhi = (int)(unsigned)(msh >> 32);
;       int mk[4][4];
; #pragma unroll
;       for (int j = 0; j < 4; ++j) {
;         mk[0][j] = __builtin_amdgcn_sbfe(mlo, j, 1); mk[1][j] = __builtin_amdgcn_sbfe(mlo, 16 + j, 1);
;         mk[2][j] = __builtin_amdgcn_sbfe(mhi, j, 1); mk[3][j] = __builtin_amdgcn_sbfe(mhi, 16 + j, 1);
;       }
; #pragma unroll
;       for (int hh = 0; hh < 2; ++hh) {
;         float mx = s[hh][0][0];
; #pragma unroll
;         for (int kq = 0; kq < 4; ++kq)
; #pragma unroll
;           for (int j = 0; j < 4; ++j) mx = fmaxf(mx, s[hh][kq][j]);
;         {
;           auto r1 = __builtin_amdgcn_permlane16_swap(__float_as_uint(mx), __float_as_uint(mx), false, false);
;           mx = fmaxf(__uint_as_float(r1[0]), __uint_as_float(r1[1]));
;           auto r2 = __builtin_amdgcn_permlane32_swap(__float_as_uint(mx), __float_as_uint(mx), false, false);
;           mx = fmaxf(__uint_as_float(r2[0]), __uint_as_float(r2[1]));
;         }
;         if (kt == 0 || __ballot(mx > 8.f)) {
;           const float delta = (kt == 0) ? mx : fmaxf(mx, 0.f);
;           const float alpha = fexp2(-delta);
;           mrun[hh] += delta;
;           lsum[hh] *= alpha;
; #pragma unroll
;           for (int dt = 0; dt < 8; ++dt) o[hh][dt] *= alpha;
; #pragma unroll
;           for (int kq = 0; kq < 4; ++kq)
; #pragma unroll
;             for (int j = 0; j < 4; ++j) s[hh][kq][j] -= delta;
;         }
.LBB0_1731:
	s_add_i32 s6, s3, 0xffffffa0
	s_cmp_gt_i32 s6, s1
	s_cbranch_scc1 .LBB0_1737
	ds_read_b128 v[116:119], v175
	ds_read_b128 v[120:123], v175 offset:64
	ds_read_b128 v[124:127], v175 offset:128
	ds_read_b128 v[128:131], v175 offset:192
	ds_read_b128 v[132:135], v175 offset:4352
	ds_read_b128 v[140:143], v175 offset:4416
	ds_read_b128 v[144:147], v175 offset:4480
	ds_read_b128 v[178:181], v175 offset:4544
	v_xor_b32_e32 v182, 0x80000000, v3
	v_xor_b32_e32 v186, 0x80000000, v2
	v_mov_b32_e32 v183, v182
	v_mov_b32_e32 v184, v182
	v_mov_b32_e32 v185, v182
	v_mov_b32_e32 v187, v186
	v_mov_b32_e32 v188, v186
	v_mov_b32_e32 v189, v186
	s_waitcnt lgkmcnt(4)
	v_mfma_f32_16x16x32_bf16 v[136:139], v[116:119], v[32:35], v[182:185]
	v_mfma_f32_16x16x32_bf16 v[116:119], v[116:119], v[16:19], v[186:189]
	v_mfma_f32_16x16x32_bf16 v[136:139], v[120:123], v[4:7], v[136:139]
	v_mfma_f32_16x16x32_bf16 v[116:119], v[120:123], v[20:23], v[116:119]
	v_mfma_f32_16x16x32_bf16 v[120:123], v[124:127], v[8:11], v[136:139]
	v_mfma_f32_16x16x32_bf16 v[116:119], v[124:127], v[24:27], v[116:119]
	v_mfma_f32_16x16x32_bf16 v[152:155], v[128:131], v[12:15], v[120:123]
	v_mfma_f32_16x16x32_bf16 v[136:139], v[128:131], v[28:31], v[116:119]
	s_nop 3
	s_nop 1
	ds_read_b128 v[116:119], v175 offset:8704
	ds_read_b128 v[120:123], v175 offset:8768
	ds_read_b128 v[124:127], v175 offset:8832
	ds_read_b128 v[128:131], v175 offset:8896
	s_waitcnt lgkmcnt(4)
	v_mfma_f32_16x16x32_bf16 v[148:151], v[132:135], v[32:35], v[182:185]
	v_mfma_f32_16x16x32_bf16 v[132:135], v[132:135], v[16:19], v[186:189]
	v_mfma_f32_16x16x32_bf16 v[148:151], v[140:143], v[4:7], v[148:151]
	v_mfma_f32_16x16x32_bf16 v[132:135], v[140:143], v[20:23], v[132:135]
	v_mfma_f32_16x16x32_bf16 v[140:143], v[144:147], v[8:11], v[148:151]
	v_mfma_f32_16x16x32_bf16 v[132:135], v[144:147], v[24:27], v[132:135]
	v_mfma_f32_16x16x32_bf16 v[148:151], v[178:181], v[12:15], v[140:143]
	v_mfma_f32_16x16x32_bf16 v[132:135], v[178:181], v[28:31], v[132:135]
	ds_read_b128 v[144:147], v175 offset:13056
	ds_read_b128 v[178:181], v175 offset:13120
	ds_read_b128 v[190:193], v175 offset:13184
	ds_read_b128 v[194:197], v175 offset:13248
	s_waitcnt lgkmcnt(4)
	v_mfma_f32_16x16x32_bf16 v[140:143], v[116:119], v[32:35], v[182:185]
	v_mfma_f32_16x16x32_bf16 v[116:119], v[116:119], v[16:19], v[186:189]
	v_mfma_f32_16x16x32_bf16 v[140:143], v[120:123], v[4:7], v[140:143]
	v_mfma_f32_16x16x32_bf16 v[116:119], v[120:123], v[20:23], v[116:119]
	v_mfma_f32_16x16x32_bf16 v[120:123], v[124:127], v[8:11], v[140:143]
	v_mfma_f32_16x16x32_bf16 v[116:119], v[124:127], v[24:27], v[116:119]
	v_mfma_f32_16x16x32_bf16 v[140:143], v[128:131], v[12:15], v[120:123]
	v_mfma_f32_16x16x32_bf16 v[124:127], v[128:131], v[28:31], v[116:119]
	s_nop 2
	s_nop 0
	s_nop 1
	ds_read_b128 v[116:119], v177 offset:17408
	ds_read_b128 v[120:123], v177 offset:17472
	s_waitcnt lgkmcnt(2)
	v_mfma_f32_16x16x32_bf16 v[128:131], v[144:147], v[32:35], v[182:185]
	v_mfma_f32_16x16x32_bf16 v[144:147], v[144:147], v[16:19], v[186:189]
	v_mfma_f32_16x16x32_bf16 v[128:131], v[178:181], v[4:7], v[128:131]
	v_mfma_f32_16x16x32_bf16 v[144:147], v[178:181], v[20:23], v[144:147]
	v_mfma_f32_16x16x32_bf16 v[128:131], v[190:193], v[8:11], v[128:131]
	v_mfma_f32_16x16x32_bf16 v[178:181], v[190:193], v[24:27], v[144:147]
	v_mfma_f32_16x16x32_bf16 v[144:147], v[194:197], v[12:15], v[128:131]
	v_mfma_f32_16x16x32_bf16 v[128:131], v[194:197], v[28:31], v[178:181]
	s_nop 3
	s_nop 1
	v_max_f32_e32 v179, v152, v152
	v_max_f32_e32 v178, v179, v153
	v_max3_f32 v178, v178, v154, v155
	v_max3_f32 v178, v178, v148, v149
	v_max3_f32 v178, v178, v150, v151
	v_max3_f32 v178, v178, v140, v141
	v_max3_f32 v178, v178, v142, v143
	v_max3_f32 v178, v178, v144, v145
	v_max3_f32 v178, v178, v146, v147
	v_mov_b32_e32 v179, v178
	s_nop 1
	v_permlane16_swap_b32_e32 v178, v179
	v_max_f32_e32 v178, v178, v179
	v_mov_b32_e32 v179, v178
	s_nop 1
	v_permlane32_swap_b32_e32 v178, v179
	v_max_f32_e32 v178, v178, v179
	v_cmp_lt_f32_e32 vcc, s28, v178
	s_cbranch_vccz .LBB0_1734
	v_max_f32_e32 v178, 0, v178
	v_exp_f32_e64 v180, -v178
	v_add_f32_e32 v3, v3, v178
	v_pk_add_f32 v[152:153], v[152:153], v[178:179] op_sel_hi:[1,0] neg_lo:[0,1] neg_hi:[0,1]
	v_pk_add_f32 v[154:155], v[154:155], v[178:179] op_sel_hi:[1,0] neg_lo:[0,1] neg_hi:[0,1]
	v_mul_f32_e32 v160, v160, v180
	v_pk_mul_f32 v[90:91], v[90:91], v[180:181] op_sel_hi:[1,0]
	v_pk_mul_f32 v[88:89], v[88:89], v[180:181] op_sel_hi:[1,0]
	v_pk_mul_f32 v[86:87], v[86:87], v[180:181] op_sel_hi:[1,0]
	v_pk_mul_f32 v[84:85], v[84:85], v[180:181] op_sel_hi:[1,0]
	v_pk_mul_f32 v[94:95], v[94:95], v[180:181] op_sel_hi:[1,0]
	v_pk_mul_f32 v[92:93], v[92:93], v[180:181] op_sel_hi:[1,0]
	v_pk_mul_f32 v[98:99], v[98:99], v[180:181] op_sel_hi:[1,0]
	v_pk_mul_f32 v[96:97], v[96:97], v[180:181] op_sel_hi:[1,0]
	v_pk_mul_f32 v[106:107], v[106:107], v[180:181] op_sel_hi:[1,0]
	v_pk_mul_f32 v[104:105], v[104:105], v[180:181] op_sel_hi:[1,0]
	v_pk_mul_f32 v[110:111], v[110:111], v[180:181] op_sel_hi:[1,0]
	v_pk_mul_f32 v[108:109], v[108:109], v[180:181] op_sel_hi:[1,0]
	v_pk_mul_f32 v[114:115], v[114:115], v[180:181] op_sel_hi:[1,0]
	v_pk_mul_f32 v[112:113], v[112:113], v[180:181] op_sel_hi:[1,0]
	v_pk_mul_f32 v[102:103], v[102:103], v[180:181] op_sel_hi:[1,0]
	v_pk_mul_f32 v[100:101], v[100:101], v[180:181] op_sel_hi:[1,0]
	v_pk_add_f32 v[148:149], v[148:149], v[178:179] op_sel_hi:[1,0] neg_lo:[0,1] neg_hi:[0,1]
	v_pk_add_f32 v[150:151], v[150:151], v[178:179] op_sel_hi:[1,0] neg_lo:[0,1] neg_hi:[0,1]
	v_pk_add_f32 v[140:141], v[140:141], v[178:179] op_sel_hi:[1,0] neg_lo:[0,1] neg_hi:[0,1]
	v_pk_add_f32 v[142:143], v[142:143], v[178:179] op_sel_hi:[1,0] neg_lo:[0,1] neg_hi:[0,1]
	v_pk_add_f32 v[144:145], v[144:145], v[178:179] op_sel_hi:[1,0] neg_lo:[0,1] neg_hi:[0,1]
	v_pk_add_f32 v[146:147], v[146:147], v[178:179] op_sel_hi:[1,0] neg_lo:[0,1] neg_hi:[0,1]
